# class-B WGs run deferred weight/cache conversions inside P2 after their lru_x tile; class A takes 7 int8 tiles; paired loads in transposes
# speedup vs baseline: 1.0043x; 1.0043x over previous
.LBB0_5:
	s_or_b64 exec, exec, s[2:3]
	s_mov_b32 s32, 0
	v_lshlrev_b32_e32 v2, 2, v0
	v_add_u32_e32 v2, 0x22080, v2
	v_writelane_b32 v3, s0, 0
	v_writelane_b32 v3, s1, 1
	v_writelane_b32 v3, s20, 2
	v_writelane_b32 v3, s76, 3
	v_writelane_b32 v3, s77, 4
	ds_write_b32 v2, v254 offset:2048
	ds_write_b32 v2, v3 offset:4096
	s_waitcnt lgkmcnt(0)
.Lmode_reentry:
	s_load_dwordx16 s[56:71], s[0:1], 0x0
	s_load_dwordx16 s[4:19], s[0:1], 0x40
	s_lshr_b32 s2, s20, 6
	s_lshl_b32 s78, s96, 3
	s_mov_b32 s88, s2
	v_and_b32_e32 v1, 63, v0
	s_waitcnt lgkmcnt(0)
	v_writelane_b32 v254, s4, 19
	s_nop 1
	v_writelane_b32 v254, s5, 20
	v_writelane_b32 v254, s6, 21
	v_writelane_b32 v254, s7, 22
	v_writelane_b32 v254, s8, 23
	v_writelane_b32 v254, s9, 24
	v_writelane_b32 v254, s10, 25
	v_writelane_b32 v254, s11, 26
	v_writelane_b32 v254, s12, 27
	v_writelane_b32 v254, s13, 28
	v_writelane_b32 v254, s14, 29
	v_writelane_b32 v254, s15, 30
	v_writelane_b32 v254, s16, 31
	v_writelane_b32 v254, s17, 32
	v_writelane_b32 v254, s18, 33
	v_writelane_b32 v254, s19, 34
	s_load_dwordx16 s[4:19], s[0:1], 0x80
	s_lshl_b32 s0, s97, 3
	s_add_i32 s0, s2, s0
	s_waitcnt lgkmcnt(0)
	v_writelane_b32 v254, s4, 35
	s_nop 1
	v_writelane_b32 v254, s5, 36
	v_writelane_b32 v254, s6, 37
	v_writelane_b32 v254, s7, 38
	v_writelane_b32 v254, s8, 39
	v_writelane_b32 v254, s9, 40
	v_writelane_b32 v254, s10, 41
	v_writelane_b32 v254, s11, 42
	v_writelane_b32 v254, s12, 43
	v_writelane_b32 v254, s13, 44
	v_writelane_b32 v254, s14, 45
	v_writelane_b32 v254, s15, 46
	v_writelane_b32 v254, s16, 47
	v_writelane_b32 v254, s17, 48
	v_writelane_b32 v254, s18, 49
	v_writelane_b32 v254, s19, 50
	v_writelane_b32 v254, s20, 51
	v_writelane_b32 v254, s0, 52
	s_nop 1
	v_writelane_b32 v254, s1, 53
	s_add_u32 s0, s76, 0x100000
	v_writelane_b32 v254, s0, 54
	s_addc_u32 s0, s77, 0
	v_writelane_b32 v254, s0, 55
	s_nop 0
	v_readlane_b32 s0, v254, 10
	v_readlane_b32 s2, v254, 12
	v_readlane_b32 s1, v254, 11
	s_mov_b32 s6, s2
	s_mov_b64 s[4:5], s[0:1]
	s_cmp_lt_i32 s4, 1
	v_readlane_b32 s3, v254, 13
	s_cselect_b64 s[0:1], -1, 0
	s_cmp_gt_i32 s5, 0
	s_cselect_b64 s[2:3], -1, 0
	s_and_b64 s[0:1], s[0:1], s[2:3]
	s_andn2_b64 vcc, exec, s[0:1]
	s_mov_b32 s0, s96
	v_writelane_b32 v254, s0, 56
	s_nop 1
	v_writelane_b32 v254, s1, 57
	v_writelane_b32 v254, s76, 58
	s_nop 1
	v_writelane_b32 v254, s77, 59
	v_writelane_b32 v254, s97, 60
	s_cbranch_vccnz .LBB0_175
	s_mov_b32 s36, s78
	v_writelane_b32 v254, s36, 61
	s_add_u32 s72, s76, 0x8000
	s_addc_u32 s73, s77, 0
	v_writelane_b32 v254, s37, 62
	s_mov_b32 s12, s88
	v_readlane_b32 s10, v254, 52
	s_cmpk_lt_i32 s10, 0x1580
	s_cselect_b64 s[0:1], -1, 0
	v_readlane_b32 s11, v254, 53
	v_writelane_b32 v254, s0, 63
	s_mov_b32 s8, s96
	v_readlane_b32 s2, v254, 16
	v_writelane_b32 v255, s1, 0
	s_add_u32 s0, s76, 0x4200
	s_addc_u32 s1, s77, 0
	s_add_u32 s92, s76, 0x4400
	s_addc_u32 s93, s77, 0
	s_add_u32 s94, s76, 0x4500
	s_addc_u32 s95, s77, 0
	s_add_u32 s88, s76, 0x4600
	s_addc_u32 s89, s77, 0
	s_add_u32 s74, s76, 0x4700
	s_addc_u32 s75, s77, 0
	s_add_u32 s16, s76, 0x4800
	s_addc_u32 s17, s77, 0
	s_add_u32 s18, s76, 0x4900
	s_addc_u32 s19, s77, 0
	s_add_u32 s20, s76, 0x4a00
	s_addc_u32 s21, s77, 0
	s_add_u32 s22, s76, 0x4b00
	s_addc_u32 s23, s77, 0
	s_add_u32 s24, s76, 0x4c00
	s_addc_u32 s25, s77, 0
	s_add_u32 s26, s76, 0x4d00
	s_addc_u32 s27, s77, 0
	s_add_u32 s28, s76, 0x4e00
	s_addc_u32 s29, s77, 0
	s_add_u32 s30, s76, 0x4f00
	s_addc_u32 s31, s77, 0
	s_add_u32 s34, s76, 0x5000
	s_addc_u32 s35, s77, 0
	s_add_u32 s6, s76, 0x5100
	s_addc_u32 s7, s77, 0
	s_add_u32 s38, s76, 0x5200
	s_addc_u32 s39, s77, 0
	s_add_u32 s96, s76, 0x5300
	s_addc_u32 s97, s77, 0
	s_cmp_eq_u32 s2, 15
	s_cselect_b64 s[14:15], -1, 0
	v_writelane_b32 v255, s14, 1
	s_cmp_eq_u32 s2, 14
	v_readlane_b32 s4, v254, 14
	v_writelane_b32 v255, s15, 2
	s_cselect_b64 s[14:15], -1, 0
	v_writelane_b32 v255, s14, 3
	s_cmp_eq_u32 s2, 13
	v_readlane_b32 s5, v254, 15
	v_writelane_b32 v255, s15, 4
	s_cselect_b64 s[14:15], -1, 0
	v_writelane_b32 v255, s14, 5
	s_cmp_eq_u32 s2, 12
	v_lshrrev_b32_e32 v170, 3, v1
	v_writelane_b32 v255, s15, 6
	s_cselect_b64 s[14:15], -1, 0
	v_writelane_b32 v255, s14, 7
	s_cmp_eq_u32 s2, 11
	v_mov_b32_e32 v3, 0x6b800
	v_writelane_b32 v255, s15, 8
	s_cselect_b64 s[14:15], -1, 0
	v_writelane_b32 v255, s14, 9
	s_cmp_eq_u32 s2, 10
	v_mov_b32_e32 v2, 0x56000
	v_writelane_b32 v255, s15, 10
	s_cselect_b64 s[14:15], -1, 0
	v_writelane_b32 v255, s14, 11
	s_cmp_eq_u32 s2, 9
	s_mul_i32 s33, s12, 0x2200
	v_writelane_b32 v255, s15, 12
	s_cselect_b64 s[14:15], -1, 0
	v_writelane_b32 v255, s14, 13
	s_cmp_eq_u32 s2, 8
	v_and_b32_e32 v171, 7, v0
	v_writelane_b32 v255, s15, 14
	s_cselect_b64 s[14:15], -1, 0
	v_writelane_b32 v255, s14, 15
	s_cmp_eq_u32 s2, 7
	v_lshrrev_b32_e32 v148, 2, v1
	v_writelane_b32 v255, s15, 16
	s_cselect_b64 s[14:15], -1, 0
	v_writelane_b32 v255, s14, 17
	s_cmp_eq_u32 s2, 6
	v_and_b32_e32 v142, 60, v1
	v_writelane_b32 v255, s15, 18
	s_cselect_b64 s[14:15], -1, 0
	v_writelane_b32 v255, s14, 19
	s_cmp_eq_u32 s2, 5
	v_lshlrev_b32_e32 v8, 2, v1
	v_writelane_b32 v255, s15, 20
	s_cselect_b64 s[14:15], -1, 0
	v_writelane_b32 v255, s14, 21
	s_cmp_eq_u32 s2, 4
	v_mov_b32_e32 v143, 0
	v_writelane_b32 v255, s15, 22
	s_cselect_b64 s[14:15], -1, 0
	v_writelane_b32 v255, s14, 23
	s_cmp_eq_u32 s2, 3
	v_lshlrev_b32_e32 v12, 2, v171
	v_writelane_b32 v255, s15, 24
	s_cselect_b64 s[14:15], -1, 0
	v_writelane_b32 v255, s14, 25
	s_cmp_eq_u32 s2, 2
	v_mul_u32_u24_e32 v14, 0x2b00, v170
	v_writelane_b32 v255, s15, 26
	s_cselect_b64 s[14:15], -1, 0
	v_writelane_b32 v255, s14, 27
	s_cmp_eq_u32 s2, 1
	v_lshlrev_b32_e32 v172, 3, v1
	v_writelane_b32 v255, s15, 28
	s_cselect_b64 s[14:15], -1, 0
	v_writelane_b32 v255, s14, 29
	s_cmp_eq_u32 s2, 0
	v_and_b32_e32 v32, 0x7c, v8
	v_writelane_b32 v255, s15, 30
	s_cselect_b64 s[14:15], -1, 0
	s_lshl_b32 s2, s2, 8
	s_add_u32 s2, s4, s2
	s_addc_u32 s3, s5, 0
	v_writelane_b32 v255, s14, 31
	s_add_u32 s4, s2, 0x1400
	s_addc_u32 s5, s3, 0
	v_writelane_b32 v255, s15, 32
	v_writelane_b32 v255, s4, 33
	s_add_u32 s2, s2, 0x2400
	s_addc_u32 s3, s3, 0
	v_writelane_b32 v255, s5, 34
	s_movk_i32 s4, 0x2b00
	v_mad_u32_u24 v4, v170, s4, v3
	v_mov_b32_e32 v3, 0x81000
	v_mad_u32_u24 v18, v170, s4, v3
	v_mov_b32_e32 v3, 0x96800
	v_mad_u32_u24 v2, v170, s4, v2
	v_mad_u32_u24 v20, v170, s4, v3
	s_add_u32 s4, s76, 0x7400
	s_addc_u32 s5, s77, 0
	v_writelane_b32 v255, s4, 35
	s_mov_b32 s14, s12
	v_lshlrev_b32_e32 v3, 4, v0
	v_writelane_b32 v255, s5, 36
	s_add_u32 s4, s76, 0x7500
	s_addc_u32 s5, s77, 0
	s_add_u32 s51, s76, 0x7600000
	s_addc_u32 s52, s77, 0
	s_cmpk_lt_i32 s10, 0x5600
	v_writelane_b32 v255, s14, 37
	v_and_b32_e32 v144, 48, v3
	s_cselect_b64 s[76:77], -1, 0
	v_writelane_b32 v255, s15, 38
	s_add_i32 s9, s33, 0
	v_mul_u32_u24_e32 v3, 0x84, v144
	v_writelane_b32 v255, s9, 39
	v_add3_u32 v149, s9, v3, v142
	v_or_b32_e32 v3, 16, v148
	s_add_i32 s91, 0, 0x22024
	v_lshl_add_u32 v30, v171, 4, s9
	v_mul_u32_u24_e32 v31, 0x84, v170
	v_mov_b32_e32 v145, v143
	v_lshlrev_b32_e32 v6, 12, v148
	v_mov_b32_e32 v7, v143
	v_lshlrev_b32_e32 v146, 12, v3
	v_mov_b32_e32 v147, v143
	v_lshl_add_u64 v[10:11], s[72:73], 0, v[142:143]
	v_lshlrev_b32_e32 v8, 2, v8
	v_mov_b32_e32 v9, v143
	v_mov_b32_e32 v33, 1
	v_lshlrev_b32_e32 v142, 2, v12
	v_lshlrev_b32_e32 v12, 2, v14
	v_lshlrev_b32_e32 v14, 2, v2
	v_lshlrev_b32_e32 v16, 2, v4
	v_lshlrev_b32_e32 v18, 2, v18
	v_lshlrev_b32_e32 v20, 2, v20
	v_lshl_or_b32 v34, s10, 9, v172
	s_mov_b32 s53, 0x56000
	s_lshl_b32 s54, s8, 12
	s_lshl_b32 s50, s8, 11
	s_lshl_b32 s37, s8, 8
	s_lshl_b32 s55, s8, 9
	s_mov_b32 s79, 0xac000
	s_mov_b32 s33, 0x102000
	s_add_i32 s36, 0, 0x22020
	s_mov_b32 s90, 0x42fe0000
	s_mov_b64 s[80:81], -1
	s_mov_b32 s78, 0x4b400000
	v_writelane_b32 v255, s91, 40
	s_cmp_eq_u32 s32, 0
	s_cbranch_scc1 .LBB0_66
	s_branch .LBB0_8

.LBB0_11:
	s_waitcnt vmcnt(0)
	v_readlane_b32 s8, v254, 17
	v_readlane_b32 s9, v254, 18
	s_barrier
	s_and_saveexec_b64 s[82:83], s[8:9]
	s_cbranch_execz .LBB0_63
	s_cmp_eq_u32 s32, 0
	s_cbranch_scc1 .Lg2_orig
	v_readlane_b32 s40, v254, 58
	v_readlane_b32 s41, v254, 59
	s_movk_i32 s46, 0x90
	s_cmp_eq_u32 s80, 0
	s_cselect_b32 s47, 1, 0
	s_lshl_b32 s46, s46, s47
	s_mov_b32 s47, 0
	buffer_wbl2 sc1
	s_waitcnt vmcnt(0)
	v_mov_b32_e32 v2, 0
	v_mov_b32_e32 v3, 1
	s_nop 4
	global_atomic_add v2, v3, s[40:41] offset:1536
	s_waitcnt vmcnt(0)
.Lcb_spin:
	global_load_dword v4, v2, s[40:41] offset:1536 sc1
	s_add_i32 s47, s47, 1
	s_waitcnt vmcnt(0)
	v_cmp_le_u32_e32 vcc, s46, v4
	s_cbranch_vccnz .Lcb_done
	s_sleep 2
	s_cmp_lt_u32 s47, 0x10000
	s_cbranch_scc1 .Lcb_spin
.Lcb_done:
	buffer_inv sc1
	s_waitcnt vmcnt(0)
	s_branch .LBB0_63
.Lg2_orig:
	v_mov_b32_e32 v2, s36
	s_waitcnt vmcnt(0) expcnt(0) lgkmcnt(0)
	ds_read_b32 v4, v2
	v_mov_b32_e32 v2, s91
	ds_read_b32 v2, v2
	s_waitcnt lgkmcnt(1)
	v_cmp_ne_u32_e32 vcc, 0, v4
	s_cbranch_vccnz .LBB0_27
	v_readlane_b32 s8, v254, 8
	v_readlane_b32 s9, v254, 9
	s_load_dwordx2 s[40:41], s[8:9], 0x4
	v_readlane_b32 s8, v254, 56
	s_mov_b32 s47, 1
	v_readlane_b32 s9, v254, 57
	s_waitcnt lgkmcnt(0)
	s_mul_i32 s46, s40, s8
	s_mul_i32 s46, s46, s41
	s_branch .LBB0_15

.LBB0_66:
	s_cmp_eq_u32 s32, 0
	s_cbranch_scc1 .Lg3_mode0
	v_readlane_b32 s76, v254, 58
	v_readlane_b32 s77, v254, 59
	v_readlane_b32 s78, v254, 61
	v_readlane_b32 s88, v255, 37
	v_readlane_b32 s96, v254, 56
	v_readlane_b32 s97, v254, 60
	s_nop 3
	s_add_u32 s10, s76, 0x600000
	s_addc_u32 s11, s77, 0
	v_or_b32_e32 v176, 8, v170
	v_or_b32_e32 v175, 16, v170
	v_or_b32_e32 v174, 24, v170
	v_add_u32_e32 v173, v30, v31
	s_branch .Lsec5_entry

.Lsec5_entry:
	s_add_u32 s6, s76, 0x5600000
	v_and_b32_e32 v46, 0x78, v172
	v_mov_b32_e32 v143, 0
	s_addc_u32 s7, s77, 0
	v_lshlrev_b32_e32 v2, 1, v46
	v_mov_b32_e32 v3, v143
	s_add_u32 s8, s76, 0x12200000
	v_or_b32_e32 v11, 40, v170
	v_lshl_add_u64 v[2:3], s[76:77], 0, v[2:3]
	s_mov_b64 s[0:1], 0x20000000
	s_addc_u32 s9, s77, 0
	v_lshl_add_u64 v[2:3], v[2:3], 0, s[0:1]
	v_lshlrev_b32_e32 v50, 7, v11
	v_mul_u32_u24_e32 v7, 0x420, v171
	v_lshlrev_b32_e32 v16, 2, v170
	v_readlane_b32 s0, v255, 39
	v_lshlrev_b32_e32 v58, 11, v11
	v_lshlrev_b32_e32 v11, 10, v0
	s_add_u32 s12, s76, 0x500000
	v_or_b32_e32 v9, 32, v170
	v_add3_u32 v7, s0, v7, v16
	v_and_b32_e32 v64, 0x1000, v11
	s_movk_i32 s0, 0x2800
	v_mov_b32_e32 v11, 0x3c000
	s_addc_u32 s13, s77, 0
	v_or_b32_e32 v13, 48, v170
	v_or_b32_e32 v15, 56, v170
	v_mad_u32_u24 v68, v9, s0, v11
	v_readlane_b32 s0, v254, 52
	s_add_u32 s14, s76, 0x24000000
	v_lshlrev_b32_e32 v48, 7, v9
	v_lshlrev_b32_e32 v52, 7, v13
	v_lshlrev_b32_e32 v54, 7, v15
	v_lshlrev_b32_e32 v56, 11, v9
	v_lshlrev_b32_e32 v60, 11, v13
	v_lshlrev_b32_e32 v62, 11, v15
	v_mul_u32_u24_e32 v66, 0x2800, v9
	v_readlane_b32 s1, v254, 53
	s_addc_u32 s15, s77, 0
	v_lshrrev_b32_e32 v5, 4, v1
	v_lshlrev_b32_e32 v4, 7, v170
	v_lshlrev_b32_e32 v6, 7, v176
	v_lshlrev_b32_e32 v8, 7, v175
	v_lshlrev_b32_e32 v10, 7, v174
	v_and_b32_e32 v12, 32, v172
	v_and_b32_e32 v14, 24, v172
	v_lshlrev_b32_e32 v16, 13, v170
	v_mov_b32_e32 v17, v143
	v_lshlrev_b32_e32 v18, 13, v176
	v_mov_b32_e32 v19, v143
	v_lshlrev_b32_e32 v20, 13, v175
	v_mov_b32_e32 v21, v143
	v_lshlrev_b32_e32 v22, 13, v174
	v_mov_b32_e32 v23, v143
	v_lshlrev_b32_e32 v24, 6, v170
	v_mov_b32_e32 v25, v143
	v_lshlrev_b32_e32 v26, 6, v176
	v_mov_b32_e32 v27, v143
	v_lshlrev_b32_e32 v28, 6, v175
	v_mov_b32_e32 v29, v143
	v_lshlrev_b32_e32 v30, 6, v174
	v_mov_b32_e32 v31, v143
	v_lshlrev_b32_e32 v32, 12, v170
	v_mul_u32_u24_e32 v34, 0x2b00, v148
	v_mov_b32_e32 v35, v143
	v_lshlrev_b32_e32 v36, 12, v148
	v_mov_b32_e32 v37, v143
	v_mov_b32_e32 v147, v143
	v_mul_hi_u32_u24_e32 v39, 0xa000, v170
	v_mul_u32_u24_e32 v38, 0xa000, v170
	v_mul_hi_u32_u24_e32 v41, 0xa000, v176
	v_mul_u32_u24_e32 v40, 0xa000, v176
	v_mul_hi_u32_u24_e32 v43, 0xa000, v175
	v_mul_u32_u24_e32 v42, 0xa000, v175
	v_mul_hi_u32_u24_e32 v45, 0xa000, v174
	v_mul_u32_u24_e32 v44, 0xa000, v174
	s_lshl_b32 s16, s0, 5
	s_lshl_b32 s17, s0, 4
	s_lshl_b32 s18, s96, 7
	s_mov_b32 s1, 0
	v_lshlrev_b32_e32 v46, 2, v46
	s_movk_i32 s19, 0x7fff
	s_mov_b32 s20, 0xffff0000
	s_mov_b32 s21, 0xffff5980
	v_lshlrev_b32_e32 v48, 2, v48
	v_lshlrev_b32_e32 v50, 2, v50
	v_lshlrev_b32_e32 v52, 2, v52
	v_lshlrev_b32_e32 v54, 2, v54
	v_lshlrev_b32_e32 v56, 2, v56
	v_lshlrev_b32_e32 v58, 2, v58
	v_lshlrev_b32_e32 v60, 2, v60
	v_lshlrev_b32_e32 v62, 2, v62
	v_lshlrev_b32_e32 v64, 1, v64
	s_mov_b32 s22, 0x20000
	s_mov_b32 s23, 0x40000
	s_mov_b32 s24, 0x60000
	s_mov_b32 s25, 0x80000
	s_mov_b32 s26, 0xa0000
	s_mov_b32 s27, 0xc0000
	s_mov_b32 s28, 0xe0000
	s_mov_b32 s29, 0xc3e00000
	v_lshlrev_b32_e32 v66, 2, v66
	s_mov_b32 s30, 0x50000
	v_lshlrev_b32_e32 v68, 2, v68
	v_mov_b32_e32 v9, 0x43e00000
	s_mov_b32 s31, s0
	s_branch .LBB0_155

.LBB0_155:
	s_cmpk_gt_u32 s31, 0xfff
	s_cbranch_scc0 .Lg4_nd
	s_sub_i32 s36, s31, 0xa600
	s_cmpk_lt_u32 s36, 0x100
	s_cbranch_scc1 .Lg4_nd
	s_cmp_eq_u32 s32, 0
	s_cbranch_scc1 .LBB0_154
	s_branch .Lg4_go
.Lg4_nd:
	s_cmp_lg_u32 s32, 0
	s_cbranch_scc1 .LBB0_154
.Lg4_go:
	s_cmpk_gt_i32 s31, 0xfff
	s_mov_b64 s[2:3], -1
	s_cbranch_scc0 .LBB0_173
	s_cmpk_gt_u32 s31, 0x2fff
	s_cbranch_scc0 .LBB0_170
	s_cmpk_gt_u32 s31, 0x85ff
	s_cbranch_scc0 .LBB0_167
	s_cmpk_gt_u32 s31, 0xa5ff
	s_cbranch_scc0 .LBB0_164
	s_cmpk_gt_u32 s31, 0xa6ff
	s_cbranch_scc0 .LBB0_161
	s_add_i32 s0, s31, 0xffff5900
	s_and_b32 s2, s17, 0x1f0
	s_and_b32 s4, s0, 0xfffffe00
	v_or_b32_e32 v11, s2, v5
	v_or_b32_e32 v70, s4, v11
	v_mov_b32_e32 v71, v143
	v_lshlrev_b64 v[70:71], 13, v[70:71]
	s_lshl_b32 s2, s0, 4
	v_lshl_add_u64 v[70:71], s[60:61], 0, v[70:71]
	s_and_b32 s2, s2, 0x1e00
	s_mov_b32 s3, s1
	v_lshl_add_u64 v[70:71], v[70:71], 0, s[2:3]
	v_mov_b32_e32 v47, v143
	v_lshl_add_u64 v[74:75], v[70:71], 0, v[46:47]
	s_mov_b32 s68, 0x8000
	s_mov_b32 s69, 0
	v_lshl_add_u64 v[212:213], v[74:75], 0, s[68:69]
	v_lshl_add_u64 v[214:215], v[212:213], 0, s[68:69]
	v_lshl_add_u64 v[216:217], v[214:215], 0, s[68:69]
	global_load_dwordx4 v[220:223], v[74:75], off
	global_load_dwordx4 v[224:227], v[74:75], off offset:16
	global_load_dwordx4 v[228:231], v[212:213], off
	global_load_dwordx4 v[232:235], v[212:213], off offset:16
	global_load_dwordx4 v[236:239], v[214:215], off
	global_load_dwordx4 v[240:243], v[214:215], off offset:16
	global_load_dwordx4 v[244:247], v[216:217], off
	global_load_dwordx4 v[248:251], v[216:217], off offset:16
	s_lshr_b32 s0, s0, 5
	s_lshl_b64 s[34:35], s[0:1], 17
	v_mov_b32_e32 v79, v143
	v_lshlrev_b32_e32 v78, 8, v11
	v_lshl_add_u64 v[82:83], v[2:3], 0, s[34:35]
	v_lshl_add_u64 v[78:79], v[82:83], 0, v[78:79]
	s_mov_b64 s[2:3], 0
	s_waitcnt vmcnt(6)
	v_bfe_u32 v209, v220, 16, 1
	v_bfe_u32 v210, v221, 16, 1
	v_add3_u32 v209, v220, v209, s19
	v_add3_u32 v210, v221, v210, s19
	v_lshrrev_b32_e32 v209, 16, v209
	v_and_or_b32 v220, v210, s20, v209
	v_bfe_u32 v209, v222, 16, 1
	v_bfe_u32 v210, v223, 16, 1
	v_add3_u32 v209, v222, v209, s19
	v_add3_u32 v210, v223, v210, s19
	v_lshrrev_b32_e32 v209, 16, v209
	v_and_or_b32 v221, v210, s20, v209
	v_bfe_u32 v209, v224, 16, 1
	v_bfe_u32 v210, v225, 16, 1
	v_add3_u32 v209, v224, v209, s19
	v_add3_u32 v210, v225, v210, s19
	v_lshrrev_b32_e32 v209, 16, v209
	v_and_or_b32 v222, v210, s20, v209
	v_bfe_u32 v209, v226, 16, 1
	v_bfe_u32 v210, v227, 16, 1
	v_add3_u32 v209, v226, v209, s19
	v_add3_u32 v210, v227, v210, s19
	v_lshrrev_b32_e32 v209, 16, v209
	v_and_or_b32 v223, v210, s20, v209
	global_store_dwordx4 v[78:79], v[220:223], off
	s_waitcnt vmcnt(5)
	v_bfe_u32 v209, v228, 16, 1
	v_bfe_u32 v210, v229, 16, 1
	v_add3_u32 v209, v228, v209, s19
	v_add3_u32 v210, v229, v210, s19
	v_lshrrev_b32_e32 v209, 16, v209
	v_and_or_b32 v228, v210, s20, v209
	v_bfe_u32 v209, v230, 16, 1
	v_bfe_u32 v210, v231, 16, 1
	v_add3_u32 v209, v230, v209, s19
	v_add3_u32 v210, v231, v210, s19
	v_lshrrev_b32_e32 v209, 16, v209
	v_and_or_b32 v229, v210, s20, v209
	v_bfe_u32 v209, v232, 16, 1
	v_bfe_u32 v210, v233, 16, 1
	v_add3_u32 v209, v232, v209, s19
	v_add3_u32 v210, v233, v210, s19
	v_lshrrev_b32_e32 v209, 16, v209
	v_and_or_b32 v230, v210, s20, v209
	v_bfe_u32 v209, v234, 16, 1
	v_bfe_u32 v210, v235, 16, 1
	v_add3_u32 v209, v234, v209, s19
	v_add3_u32 v210, v235, v210, s19
	v_lshrrev_b32_e32 v209, 16, v209
	v_and_or_b32 v231, v210, s20, v209
	global_store_dwordx4 v[78:79], v[228:231], off offset:1024
	s_waitcnt vmcnt(4)
	v_bfe_u32 v209, v236, 16, 1
	v_bfe_u32 v210, v237, 16, 1
	v_add3_u32 v209, v236, v209, s19
	v_add3_u32 v210, v237, v210, s19
	v_lshrrev_b32_e32 v209, 16, v209
	v_and_or_b32 v236, v210, s20, v209
	v_bfe_u32 v209, v238, 16, 1
	v_bfe_u32 v210, v239, 16, 1
	v_add3_u32 v209, v238, v209, s19
	v_add3_u32 v210, v239, v210, s19
	v_lshrrev_b32_e32 v209, 16, v209
	v_and_or_b32 v237, v210, s20, v209
	v_bfe_u32 v209, v240, 16, 1
	v_bfe_u32 v210, v241, 16, 1
	v_add3_u32 v209, v240, v209, s19
	v_add3_u32 v210, v241, v210, s19
	v_lshrrev_b32_e32 v209, 16, v209
	v_and_or_b32 v238, v210, s20, v209
	v_bfe_u32 v209, v242, 16, 1
	v_bfe_u32 v210, v243, 16, 1
	v_add3_u32 v209, v242, v209, s19
	v_add3_u32 v210, v243, v210, s19
	v_lshrrev_b32_e32 v209, 16, v209
	v_and_or_b32 v239, v210, s20, v209
	global_store_dwordx4 v[78:79], v[236:239], off offset:2048
	s_waitcnt vmcnt(3)
	v_bfe_u32 v209, v244, 16, 1
	v_bfe_u32 v210, v245, 16, 1
	v_add3_u32 v209, v244, v209, s19
	v_add3_u32 v210, v245, v210, s19
	v_lshrrev_b32_e32 v209, 16, v209
	v_and_or_b32 v244, v210, s20, v209
	v_bfe_u32 v209, v246, 16, 1
	v_bfe_u32 v210, v247, 16, 1
	v_add3_u32 v209, v246, v209, s19
	v_add3_u32 v210, v247, v210, s19
	v_lshrrev_b32_e32 v209, 16, v209
	v_and_or_b32 v245, v210, s20, v209
	v_bfe_u32 v209, v248, 16, 1
	v_bfe_u32 v210, v249, 16, 1
	v_add3_u32 v209, v248, v209, s19
	v_add3_u32 v210, v249, v210, s19
	v_lshrrev_b32_e32 v209, 16, v209
	v_and_or_b32 v246, v210, s20, v209
	v_bfe_u32 v209, v250, 16, 1
	v_bfe_u32 v210, v251, 16, 1
	v_add3_u32 v209, v250, v209, s19
	v_add3_u32 v210, v251, v210, s19
	v_lshrrev_b32_e32 v209, 16, v209
	v_and_or_b32 v247, v210, s20, v209
	global_store_dwordx4 v[78:79], v[244:247], off offset:3072

.LBB0_164:
	s_andn2_b64 vcc, exec, s[2:3]
	s_cbranch_vccnz .LBB0_166
	s_add_i32 s36, s31, s78
	s_cmp_gt_u32 s36, 0xa5ff
	s_cbranch_scc1 .Lk_CVT_single
	s_add_i32 s4, s31, 0xffff7a00
	s_bfe_u32 s33, s31, 0x30002
	s_and_b32 s0, s4, 0xfffffe00
	s_lshl_b32 s2, s33, 6
	s_or_b32 s0, s2, s0
	s_bfe_u32 s5, s31, 0x40005
	s_lshl_b64 s[2:3], s[0:1], 13
	s_add_u32 s0, s62, s2
	s_addc_u32 s2, s63, s3
	s_lshl_b32 s3, s5, 9
	s_add_u32 s0, s0, s3
	s_addc_u32 s3, s2, 0
	s_and_b32 s34, s16, 0x60
	s_lshl_b32 s2, s34, 2
	s_add_u32 s2, s0, s2
	s_addc_u32 s3, s3, 0
	v_lshl_add_u64 v[98:99], s[2:3], 0, v[142:143]
	v_mov_b32_e32 v57, v143
	v_mov_b32_e32 v59, v143
	v_lshl_add_u64 v[70:71], v[98:99], 0, v[16:17]
	v_lshl_add_u64 v[74:75], v[98:99], 0, v[18:19]
	v_lshl_add_u64 v[78:79], v[98:99], 0, v[20:21]
	v_lshl_add_u64 v[82:83], v[98:99], 0, v[22:23]
	v_lshl_add_u64 v[86:87], v[98:99], 0, v[56:57]
	v_lshl_add_u64 v[90:91], v[98:99], 0, v[58:59]
	global_load_dwordx4 v[70:73], v[70:71], off
	s_nop 0
	global_load_dwordx4 v[74:77], v[74:75], off
	s_nop 0
	global_load_dwordx4 v[78:81], v[78:79], off
	s_nop 0
	global_load_dwordx4 v[82:85], v[82:83], off
	s_nop 0
	global_load_dwordx4 v[86:89], v[86:87], off
	s_nop 0
	global_load_dwordx4 v[90:93], v[90:91], off
	v_mov_b32_e32 v61, v143
	v_lshl_add_u64 v[94:95], v[98:99], 0, v[60:61]
	global_load_dwordx4 v[94:97], v[94:95], off
	v_mov_b32_e32 v63, v143
	v_lshl_add_u64 v[98:99], v[98:99], 0, v[62:63]
	global_load_dwordx4 v[98:101], v[98:99], off
	s_add_i32 s31, s31, s78
	s_add_i32 s16, s16, s37
	s_add_i32 s17, s17, s18
	s_mov_b32 s69, 0
	s_add_i32 s72, s31, 0xffff7a00
	s_bfe_u32 s79, s31, 0x30002
	s_and_b32 s68, s72, 0xfffffe00
	s_lshl_b32 s70, s79, 6
	s_or_b32 s68, s70, s68
	s_bfe_u32 s73, s31, 0x40005
	s_lshl_b64 s[70:71], s[68:69], 13
	s_add_u32 s68, s62, s70
	s_addc_u32 s70, s63, s71
	s_lshl_b32 s71, s73, 9
	s_add_u32 s68, s68, s71
	s_addc_u32 s71, s70, 0
	s_and_b32 s74, s16, 0x60
	s_lshl_b32 s70, s74, 2
	s_add_u32 s70, s68, s70
	s_addc_u32 s71, s71, 0
	v_lshl_add_u64 v[248:249], s[70:71], 0, v[142:143]
	v_mov_b32_e32 v57, v143
	v_mov_b32_e32 v59, v143
	v_lshl_add_u64 v[220:221], v[248:249], 0, v[16:17]
	v_lshl_add_u64 v[224:225], v[248:249], 0, v[18:19]
	v_lshl_add_u64 v[228:229], v[248:249], 0, v[20:21]
	v_lshl_add_u64 v[232:233], v[248:249], 0, v[22:23]
	v_lshl_add_u64 v[236:237], v[248:249], 0, v[56:57]
	v_lshl_add_u64 v[240:241], v[248:249], 0, v[58:59]
	global_load_dwordx4 v[220:223], v[220:221], off
	s_nop 0
	global_load_dwordx4 v[224:227], v[224:225], off
	s_nop 0
	global_load_dwordx4 v[228:231], v[228:229], off
	s_nop 0
	global_load_dwordx4 v[232:235], v[232:233], off
	s_nop 0
	global_load_dwordx4 v[236:239], v[236:237], off
	s_nop 0
	global_load_dwordx4 v[240:243], v[240:241], off
	v_mov_b32_e32 v61, v143
	v_lshl_add_u64 v[244:245], v[248:249], 0, v[60:61]
	global_load_dwordx4 v[244:247], v[244:245], off
	v_mov_b32_e32 v63, v143
	v_lshl_add_u64 v[248:249], v[248:249], 0, v[62:63]
	global_load_dwordx4 v[248:251], v[248:249], off
	s_sub_i32 s31, s31, s78
	s_sub_i32 s16, s16, s37
	s_sub_i32 s17, s17, s18
	v_add_u32_e32 v11, 0x420, v173
	v_add_u32_e32 v13, 0x428, v173
	v_add_u32_e32 v15, 0x840, v173
	v_add_u32_e32 v33, 0x848, v173
	v_add_u32_e32 v47, 0xc60, v173
	v_add_u32_e32 v49, 0xc68, v173
	v_add_u32_e32 v51, 0x1080, v173
	v_add_u32_e32 v53, 0x1088, v173
	v_add_u32_e32 v55, 0x14a0, v173
	v_add_u32_e32 v57, 0x14a8, v173
	v_add_u32_e32 v59, 0x18c0, v173
	v_add_u32_e32 v61, 0x18c8, v173
	v_add_u32_e32 v63, 0x1ce0, v173
	v_add_u32_e32 v67, 0x1ce8, v173
	s_lshr_b32 s0, s4, 5
	s_and_b32 s0, s0, 0x7fffff0
	s_or_b32 s0, s0, s5
	s_lshl_b32 s2, s33, 1
	s_mul_i32 s0, s0, 17
	s_add_i32 s0, s0, s2
	s_lshl_b64 s[2:3], s[0:1], 13
	s_add_u32 s0, s14, s2
	s_addc_u32 s3, s15, s3
	s_lshl_b32 s2, s34, 6
	s_add_u32 s2, s0, s2
	v_mov_b32_e32 v65, v143
	s_addc_u32 s3, s3, 0
	v_lshlrev_b32_e32 v102, 1, v14
	v_mov_b32_e32 v103, v143
	v_lshl_add_u64 v[104:105], s[2:3], 0, v[64:65]
	v_lshl_add_u64 v[102:103], v[104:105], 0, v[102:103]
	s_waitcnt vmcnt(15)
	ds_write2_b32 v173, v70, v71 offset1:1
	ds_write2_b32 v173, v72, v73 offset0:2 offset1:3
	s_waitcnt vmcnt(14)
	ds_write2_b32 v11, v74, v75 offset1:1
	ds_write2_b32 v13, v76, v77 offset1:1
	s_waitcnt vmcnt(13)
	ds_write2_b32 v15, v78, v79 offset1:1
	ds_write2_b32 v33, v80, v81 offset1:1
	s_waitcnt vmcnt(12)
	ds_write2_b32 v47, v82, v83 offset1:1
	ds_write2_b32 v49, v84, v85 offset1:1
	s_waitcnt vmcnt(11)
	ds_write2_b32 v51, v86, v87 offset1:1
	ds_write2_b32 v53, v88, v89 offset1:1
	s_waitcnt vmcnt(10)
	ds_write2_b32 v55, v90, v91 offset1:1
	ds_write2_b32 v57, v92, v93 offset1:1
	s_waitcnt vmcnt(9)
	ds_write2_b32 v59, v94, v95 offset1:1
	ds_write2_b32 v61, v96, v97 offset1:1
	s_waitcnt vmcnt(8)
	ds_write2_b32 v63, v98, v99 offset1:1
	ds_write2_b32 v67, v100, v101 offset1:1
	s_waitcnt lgkmcnt(0)
	ds_read2_b32 v[74:75], v7 offset0:33 offset1:41
	ds_read2_b32 v[76:77], v7 offset1:8
	ds_read2_b32 v[78:79], v7 offset0:66 offset1:74
	ds_read2_b32 v[80:81], v7 offset0:99 offset1:107
	ds_read2_b32 v[82:83], v7 offset0:132 offset1:140
	ds_read2_b32 v[84:85], v7 offset0:165 offset1:173
	s_waitcnt lgkmcnt(4)
	v_bfe_u32 v11, v76, 16, 1
	ds_read2_b32 v[86:87], v7 offset0:198 offset1:206
	v_bfe_u32 v13, v74, 16, 1
	v_add3_u32 v11, v76, v11, s19
	ds_read2_b32 v[88:89], v7 offset0:231 offset1:239
	s_waitcnt lgkmcnt(3)
	v_bfe_u32 v47, v82, 16, 1
	v_add3_u32 v13, v74, v13, s19
	v_lshrrev_b32_e32 v11, 16, v11
	v_and_or_b32 v70, v13, s20, v11
	v_add3_u32 v11, v82, v47, s19
	s_waitcnt lgkmcnt(2)
	v_bfe_u32 v13, v84, 16, 1
	v_lshrrev_b32_e32 v11, 16, v11
	v_add3_u32 v13, v84, v13, s19
	v_and_or_b32 v72, v13, s20, v11
	s_waitcnt lgkmcnt(1)
	v_bfe_u32 v11, v86, 16, 1
	v_add3_u32 v11, v86, v11, s19
	s_waitcnt lgkmcnt(0)
	v_bfe_u32 v13, v88, 16, 1
	v_bfe_u32 v15, v78, 16, 1
	v_lshrrev_b32_e32 v11, 16, v11
	v_add3_u32 v13, v88, v13, s19
	v_bfe_u32 v33, v80, 16, 1
	v_add3_u32 v15, v78, v15, s19
	v_and_or_b32 v73, v13, s20, v11
	v_bfe_u32 v11, v77, 16, 1
	v_add3_u32 v33, v80, v33, s19
	v_lshrrev_b32_e32 v15, 16, v15
	v_add3_u32 v11, v77, v11, s19
	v_bfe_u32 v13, v75, 16, 1
	v_and_or_b32 v71, v33, s20, v15
	v_lshl_add_u64 v[90:91], v[102:103], 0, v[24:25]
	v_lshrrev_b32_e32 v11, 16, v11
	v_add3_u32 v13, v75, v13, s19
	global_store_dwordx4 v[90:91], v[70:73], off
	ds_read2_b32 v[74:75], v7 offset0:16 offset1:24
	v_lshl_add_u64 v[76:77], v[102:103], 0, v[26:27]
	v_and_or_b32 v70, v13, s20, v11
	v_bfe_u32 v11, v79, 16, 1
	v_add3_u32 v11, v79, v11, s19
	v_bfe_u32 v13, v81, 16, 1
	v_lshrrev_b32_e32 v11, 16, v11
	v_add3_u32 v13, v81, v13, s19
	v_and_or_b32 v71, v13, s20, v11
	v_bfe_u32 v11, v83, 16, 1
	v_add3_u32 v11, v83, v11, s19
	v_bfe_u32 v13, v85, 16, 1
	v_lshrrev_b32_e32 v11, 16, v11
	v_add3_u32 v13, v85, v13, s19
	v_and_or_b32 v72, v13, s20, v11
	v_bfe_u32 v11, v87, 16, 1
	v_add3_u32 v11, v87, v11, s19
	v_bfe_u32 v13, v89, 16, 1
	v_lshrrev_b32_e32 v11, 16, v11
	v_add3_u32 v13, v89, v13, s19
	v_and_or_b32 v73, v13, s20, v11
	global_store_dwordx4 v[76:77], v[70:73], off
	ds_read2_b32 v[76:77], v7 offset0:49 offset1:57
	ds_read2_b32 v[78:79], v7 offset0:82 offset1:90
	ds_read2_b32 v[80:81], v7 offset0:115 offset1:123
	s_waitcnt lgkmcnt(3)
	v_bfe_u32 v11, v74, 16, 1
	v_add3_u32 v11, v74, v11, s19
	s_waitcnt lgkmcnt(2)
	v_bfe_u32 v13, v76, 16, 1
	ds_read2_b32 v[82:83], v7 offset0:148 offset1:156
	v_lshrrev_b32_e32 v11, 16, v11
	v_add3_u32 v13, v76, v13, s19
	ds_read2_b32 v[84:85], v7 offset0:181 offset1:189
	v_and_or_b32 v70, v13, s20, v11
	s_waitcnt lgkmcnt(3)
	v_bfe_u32 v11, v78, 16, 1
	v_add3_u32 v11, v78, v11, s19
	s_waitcnt lgkmcnt(2)
	v_bfe_u32 v13, v80, 16, 1
	ds_read2_b32 v[86:87], v7 offset0:214 offset1:222
	v_lshrrev_b32_e32 v11, 16, v11
	v_add3_u32 v13, v80, v13, s19
	ds_read2_b32 v[88:89], v7 offset0:247 offset1:255
	v_and_or_b32 v71, v13, s20, v11
	s_waitcnt lgkmcnt(3)
	v_bfe_u32 v11, v82, 16, 1
	v_add3_u32 v11, v82, v11, s19
	s_waitcnt lgkmcnt(2)
	v_bfe_u32 v13, v84, 16, 1
	v_lshrrev_b32_e32 v11, 16, v11
	v_add3_u32 v13, v84, v13, s19
	v_and_or_b32 v72, v13, s20, v11
	s_waitcnt lgkmcnt(1)
	v_bfe_u32 v11, v86, 16, 1
	v_add3_u32 v11, v86, v11, s19
	s_waitcnt lgkmcnt(0)
	v_bfe_u32 v13, v88, 16, 1
	v_lshrrev_b32_e32 v11, 16, v11
	v_add3_u32 v13, v88, v13, s19
	v_and_or_b32 v73, v13, s20, v11
	v_bfe_u32 v11, v75, 16, 1
	v_add3_u32 v11, v75, v11, s19
	v_bfe_u32 v13, v77, 16, 1
	v_lshl_add_u64 v[90:91], v[102:103], 0, v[28:29]
	v_lshrrev_b32_e32 v11, 16, v11
	v_add3_u32 v13, v77, v13, s19
	global_store_dwordx4 v[90:91], v[70:73], off
	v_lshl_add_u64 v[74:75], v[102:103], 0, v[30:31]
	s_nop 0
	v_and_or_b32 v70, v13, s20, v11
	v_bfe_u32 v11, v79, 16, 1
	v_add3_u32 v11, v79, v11, s19
	v_bfe_u32 v13, v81, 16, 1
	v_lshrrev_b32_e32 v11, 16, v11
	v_add3_u32 v13, v81, v13, s19
	v_and_or_b32 v71, v13, s20, v11
	v_bfe_u32 v11, v83, 16, 1
	v_add3_u32 v11, v83, v11, s19
	v_bfe_u32 v13, v85, 16, 1
	v_lshrrev_b32_e32 v11, 16, v11
	v_add3_u32 v13, v85, v13, s19
	v_and_or_b32 v72, v13, s20, v11
	v_bfe_u32 v11, v87, 16, 1
	v_add3_u32 v11, v87, v11, s19
	v_bfe_u32 v13, v89, 16, 1
	v_lshrrev_b32_e32 v11, 16, v11
	v_add3_u32 v13, v89, v13, s19
	v_and_or_b32 v73, v13, s20, v11
	global_store_dwordx4 v[74:75], v[70:73], off
	s_waitcnt lgkmcnt(0)
	s_add_i32 s31, s31, s78
	s_add_i32 s16, s16, s37
	s_add_i32 s17, s17, s18
	s_add_i32 s4, s31, 0xffff7a00
	s_bfe_u32 s33, s31, 0x30002
	s_and_b32 s0, s4, 0xfffffe00
	s_lshl_b32 s2, s33, 6
	s_or_b32 s0, s2, s0
	s_bfe_u32 s5, s31, 0x40005
	s_lshl_b64 s[2:3], s[0:1], 13
	s_add_u32 s0, s62, s2
	s_addc_u32 s2, s63, s3
	s_lshl_b32 s3, s5, 9
	s_add_u32 s0, s0, s3
	s_addc_u32 s3, s2, 0
	s_and_b32 s34, s16, 0x60
	s_lshl_b32 s2, s34, 2
	s_add_u32 s2, s0, s2
	s_addc_u32 s3, s3, 0
	v_lshl_add_u64 v[98:99], s[2:3], 0, v[142:143]
	v_mov_b32_e32 v57, v143
	v_mov_b32_e32 v59, v143
	v_lshl_add_u64 v[70:71], v[98:99], 0, v[16:17]
	v_lshl_add_u64 v[74:75], v[98:99], 0, v[18:19]
	v_lshl_add_u64 v[78:79], v[98:99], 0, v[20:21]
	v_lshl_add_u64 v[82:83], v[98:99], 0, v[22:23]
	v_lshl_add_u64 v[86:87], v[98:99], 0, v[56:57]
	v_lshl_add_u64 v[90:91], v[98:99], 0, v[58:59]
	s_nop 0
	s_nop 0
	s_nop 0
	s_nop 0
	s_nop 0
	v_mov_b32_e32 v61, v143
	v_lshl_add_u64 v[94:95], v[98:99], 0, v[60:61]
	v_mov_b32_e32 v63, v143
	v_lshl_add_u64 v[98:99], v[98:99], 0, v[62:63]
	v_add_u32_e32 v11, 0x420, v173
	v_add_u32_e32 v13, 0x428, v173
	v_add_u32_e32 v15, 0x840, v173
	v_add_u32_e32 v33, 0x848, v173
	v_add_u32_e32 v47, 0xc60, v173
	v_add_u32_e32 v49, 0xc68, v173
	v_add_u32_e32 v51, 0x1080, v173
	v_add_u32_e32 v53, 0x1088, v173
	v_add_u32_e32 v55, 0x14a0, v173
	v_add_u32_e32 v57, 0x14a8, v173
	v_add_u32_e32 v59, 0x18c0, v173
	v_add_u32_e32 v61, 0x18c8, v173
	v_add_u32_e32 v63, 0x1ce0, v173
	v_add_u32_e32 v67, 0x1ce8, v173
	s_lshr_b32 s0, s4, 5
	s_and_b32 s0, s0, 0x7fffff0
	s_or_b32 s0, s0, s5
	s_lshl_b32 s2, s33, 1
	s_mul_i32 s0, s0, 17
	s_add_i32 s0, s0, s2
	s_lshl_b64 s[2:3], s[0:1], 13
	s_add_u32 s0, s14, s2
	s_addc_u32 s3, s15, s3
	s_lshl_b32 s2, s34, 6
	s_add_u32 s2, s0, s2
	v_mov_b32_e32 v65, v143
	s_addc_u32 s3, s3, 0
	v_lshlrev_b32_e32 v102, 1, v14
	v_mov_b32_e32 v103, v143
	v_lshl_add_u64 v[104:105], s[2:3], 0, v[64:65]
	v_lshl_add_u64 v[102:103], v[104:105], 0, v[102:103]
	s_waitcnt vmcnt(11)
	ds_write2_b32 v173, v220, v221 offset1:1
	ds_write2_b32 v173, v222, v223 offset0:2 offset1:3
	s_waitcnt vmcnt(10)
	ds_write2_b32 v11, v224, v225 offset1:1
	ds_write2_b32 v13, v226, v227 offset1:1
	s_waitcnt vmcnt(9)
	ds_write2_b32 v15, v228, v229 offset1:1
	ds_write2_b32 v33, v230, v231 offset1:1
	s_waitcnt vmcnt(8)
	ds_write2_b32 v47, v232, v233 offset1:1
	ds_write2_b32 v49, v234, v235 offset1:1
	s_waitcnt vmcnt(7)
	ds_write2_b32 v51, v236, v237 offset1:1
	ds_write2_b32 v53, v238, v239 offset1:1
	s_waitcnt vmcnt(6)
	ds_write2_b32 v55, v240, v241 offset1:1
	ds_write2_b32 v57, v242, v243 offset1:1
	s_waitcnt vmcnt(5)
	ds_write2_b32 v59, v244, v245 offset1:1
	ds_write2_b32 v61, v246, v247 offset1:1
	s_waitcnt vmcnt(4)
	ds_write2_b32 v63, v248, v249 offset1:1
	ds_write2_b32 v67, v250, v251 offset1:1
	s_waitcnt lgkmcnt(0)
	ds_read2_b32 v[74:75], v7 offset0:33 offset1:41
	ds_read2_b32 v[76:77], v7 offset1:8
	ds_read2_b32 v[78:79], v7 offset0:66 offset1:74
	ds_read2_b32 v[80:81], v7 offset0:99 offset1:107
	ds_read2_b32 v[82:83], v7 offset0:132 offset1:140
	ds_read2_b32 v[84:85], v7 offset0:165 offset1:173
	s_waitcnt lgkmcnt(4)
	v_bfe_u32 v11, v76, 16, 1
	ds_read2_b32 v[86:87], v7 offset0:198 offset1:206
	v_bfe_u32 v13, v74, 16, 1
	v_add3_u32 v11, v76, v11, s19
	ds_read2_b32 v[88:89], v7 offset0:231 offset1:239
	s_waitcnt lgkmcnt(3)
	v_bfe_u32 v47, v82, 16, 1
	v_add3_u32 v13, v74, v13, s19
	v_lshrrev_b32_e32 v11, 16, v11
	v_and_or_b32 v70, v13, s20, v11
	v_add3_u32 v11, v82, v47, s19
	s_waitcnt lgkmcnt(2)
	v_bfe_u32 v13, v84, 16, 1
	v_lshrrev_b32_e32 v11, 16, v11
	v_add3_u32 v13, v84, v13, s19
	v_and_or_b32 v72, v13, s20, v11
	s_waitcnt lgkmcnt(1)
	v_bfe_u32 v11, v86, 16, 1
	v_add3_u32 v11, v86, v11, s19
	s_waitcnt lgkmcnt(0)
	v_bfe_u32 v13, v88, 16, 1
	v_bfe_u32 v15, v78, 16, 1
	v_lshrrev_b32_e32 v11, 16, v11
	v_add3_u32 v13, v88, v13, s19
	v_bfe_u32 v33, v80, 16, 1
	v_add3_u32 v15, v78, v15, s19
	v_and_or_b32 v73, v13, s20, v11
	v_bfe_u32 v11, v77, 16, 1
	v_add3_u32 v33, v80, v33, s19
	v_lshrrev_b32_e32 v15, 16, v15
	v_add3_u32 v11, v77, v11, s19
	v_bfe_u32 v13, v75, 16, 1
	v_and_or_b32 v71, v33, s20, v15
	v_lshl_add_u64 v[90:91], v[102:103], 0, v[24:25]
	v_lshrrev_b32_e32 v11, 16, v11
	v_add3_u32 v13, v75, v13, s19
	global_store_dwordx4 v[90:91], v[70:73], off
	ds_read2_b32 v[74:75], v7 offset0:16 offset1:24
	v_lshl_add_u64 v[76:77], v[102:103], 0, v[26:27]
	v_and_or_b32 v70, v13, s20, v11
	v_bfe_u32 v11, v79, 16, 1
	v_add3_u32 v11, v79, v11, s19
	v_bfe_u32 v13, v81, 16, 1
	v_lshrrev_b32_e32 v11, 16, v11
	v_add3_u32 v13, v81, v13, s19
	v_and_or_b32 v71, v13, s20, v11
	v_bfe_u32 v11, v83, 16, 1
	v_add3_u32 v11, v83, v11, s19
	v_bfe_u32 v13, v85, 16, 1
	v_lshrrev_b32_e32 v11, 16, v11
	v_add3_u32 v13, v85, v13, s19
	v_and_or_b32 v72, v13, s20, v11
	v_bfe_u32 v11, v87, 16, 1
	v_add3_u32 v11, v87, v11, s19
	v_bfe_u32 v13, v89, 16, 1
	v_lshrrev_b32_e32 v11, 16, v11
	v_add3_u32 v13, v89, v13, s19
	v_and_or_b32 v73, v13, s20, v11
	global_store_dwordx4 v[76:77], v[70:73], off
	ds_read2_b32 v[76:77], v7 offset0:49 offset1:57
	ds_read2_b32 v[78:79], v7 offset0:82 offset1:90
	ds_read2_b32 v[80:81], v7 offset0:115 offset1:123
	s_waitcnt lgkmcnt(3)
	v_bfe_u32 v11, v74, 16, 1
	v_add3_u32 v11, v74, v11, s19
	s_waitcnt lgkmcnt(2)
	v_bfe_u32 v13, v76, 16, 1
	ds_read2_b32 v[82:83], v7 offset0:148 offset1:156
	v_lshrrev_b32_e32 v11, 16, v11
	v_add3_u32 v13, v76, v13, s19
	ds_read2_b32 v[84:85], v7 offset0:181 offset1:189
	v_and_or_b32 v70, v13, s20, v11
	s_waitcnt lgkmcnt(3)
	v_bfe_u32 v11, v78, 16, 1
	v_add3_u32 v11, v78, v11, s19
	s_waitcnt lgkmcnt(2)
	v_bfe_u32 v13, v80, 16, 1
	ds_read2_b32 v[86:87], v7 offset0:214 offset1:222
	v_lshrrev_b32_e32 v11, 16, v11
	v_add3_u32 v13, v80, v13, s19
	ds_read2_b32 v[88:89], v7 offset0:247 offset1:255
	v_and_or_b32 v71, v13, s20, v11
	s_waitcnt lgkmcnt(3)
	v_bfe_u32 v11, v82, 16, 1
	v_add3_u32 v11, v82, v11, s19
	s_waitcnt lgkmcnt(2)
	v_bfe_u32 v13, v84, 16, 1
	v_lshrrev_b32_e32 v11, 16, v11
	v_add3_u32 v13, v84, v13, s19
	v_and_or_b32 v72, v13, s20, v11
	s_waitcnt lgkmcnt(1)
	v_bfe_u32 v11, v86, 16, 1
	v_add3_u32 v11, v86, v11, s19
	s_waitcnt lgkmcnt(0)
	v_bfe_u32 v13, v88, 16, 1
	v_lshrrev_b32_e32 v11, 16, v11
	v_add3_u32 v13, v88, v13, s19
	v_and_or_b32 v73, v13, s20, v11
	v_bfe_u32 v11, v75, 16, 1
	v_add3_u32 v11, v75, v11, s19
	v_bfe_u32 v13, v77, 16, 1
	v_lshl_add_u64 v[90:91], v[102:103], 0, v[28:29]
	v_lshrrev_b32_e32 v11, 16, v11
	v_add3_u32 v13, v77, v13, s19
	global_store_dwordx4 v[90:91], v[70:73], off
	v_lshl_add_u64 v[74:75], v[102:103], 0, v[30:31]
	s_nop 0
	v_and_or_b32 v70, v13, s20, v11
	v_bfe_u32 v11, v79, 16, 1
	v_add3_u32 v11, v79, v11, s19
	v_bfe_u32 v13, v81, 16, 1
	v_lshrrev_b32_e32 v11, 16, v11
	v_add3_u32 v13, v81, v13, s19
	v_and_or_b32 v71, v13, s20, v11
	v_bfe_u32 v11, v83, 16, 1
	v_add3_u32 v11, v83, v11, s19
	v_bfe_u32 v13, v85, 16, 1
	v_lshrrev_b32_e32 v11, 16, v11
	v_add3_u32 v13, v85, v13, s19
	v_and_or_b32 v72, v13, s20, v11
	v_bfe_u32 v11, v87, 16, 1
	v_add3_u32 v11, v87, v11, s19
	v_bfe_u32 v13, v89, 16, 1
	v_lshrrev_b32_e32 v11, 16, v11
	v_add3_u32 v13, v89, v13, s19
	v_and_or_b32 v73, v13, s20, v11
	global_store_dwordx4 v[74:75], v[70:73], off
	s_waitcnt lgkmcnt(0)
	s_branch .LBB0_166
.Lk_CVT_single:
	s_add_i32 s4, s31, 0xffff7a00
	s_bfe_u32 s33, s31, 0x30002
	s_and_b32 s0, s4, 0xfffffe00
	s_lshl_b32 s2, s33, 6
	s_or_b32 s0, s2, s0
	s_bfe_u32 s5, s31, 0x40005
	s_lshl_b64 s[2:3], s[0:1], 13
	s_add_u32 s0, s62, s2
	s_addc_u32 s2, s63, s3
	s_lshl_b32 s3, s5, 9
	s_add_u32 s0, s0, s3
	s_addc_u32 s3, s2, 0
	s_and_b32 s34, s16, 0x60
	s_lshl_b32 s2, s34, 2
	s_add_u32 s2, s0, s2
	s_addc_u32 s3, s3, 0
	v_lshl_add_u64 v[98:99], s[2:3], 0, v[142:143]
	v_mov_b32_e32 v57, v143
	v_mov_b32_e32 v59, v143
	v_lshl_add_u64 v[70:71], v[98:99], 0, v[16:17]
	v_lshl_add_u64 v[74:75], v[98:99], 0, v[18:19]
	v_lshl_add_u64 v[78:79], v[98:99], 0, v[20:21]
	v_lshl_add_u64 v[82:83], v[98:99], 0, v[22:23]
	v_lshl_add_u64 v[86:87], v[98:99], 0, v[56:57]
	v_lshl_add_u64 v[90:91], v[98:99], 0, v[58:59]
	global_load_dwordx4 v[70:73], v[70:71], off
	s_nop 0
	global_load_dwordx4 v[74:77], v[74:75], off
	s_nop 0
	global_load_dwordx4 v[78:81], v[78:79], off
	s_nop 0
	global_load_dwordx4 v[82:85], v[82:83], off
	s_nop 0
	global_load_dwordx4 v[86:89], v[86:87], off
	s_nop 0
	global_load_dwordx4 v[90:93], v[90:91], off
	v_mov_b32_e32 v61, v143
	v_lshl_add_u64 v[94:95], v[98:99], 0, v[60:61]
	global_load_dwordx4 v[94:97], v[94:95], off
	v_mov_b32_e32 v63, v143
	v_lshl_add_u64 v[98:99], v[98:99], 0, v[62:63]
	global_load_dwordx4 v[98:101], v[98:99], off
	v_add_u32_e32 v11, 0x420, v173
	v_add_u32_e32 v13, 0x428, v173
	v_add_u32_e32 v15, 0x840, v173
	v_add_u32_e32 v33, 0x848, v173
	v_add_u32_e32 v47, 0xc60, v173
	v_add_u32_e32 v49, 0xc68, v173
	v_add_u32_e32 v51, 0x1080, v173
	v_add_u32_e32 v53, 0x1088, v173
	v_add_u32_e32 v55, 0x14a0, v173
	v_add_u32_e32 v57, 0x14a8, v173
	v_add_u32_e32 v59, 0x18c0, v173
	v_add_u32_e32 v61, 0x18c8, v173
	v_add_u32_e32 v63, 0x1ce0, v173
	v_add_u32_e32 v67, 0x1ce8, v173
	s_lshr_b32 s0, s4, 5
	s_and_b32 s0, s0, 0x7fffff0
	s_or_b32 s0, s0, s5
	s_lshl_b32 s2, s33, 1
	s_mul_i32 s0, s0, 17
	s_add_i32 s0, s0, s2
	s_lshl_b64 s[2:3], s[0:1], 13
	s_add_u32 s0, s14, s2
	s_addc_u32 s3, s15, s3
	s_lshl_b32 s2, s34, 6
	s_add_u32 s2, s0, s2
	v_mov_b32_e32 v65, v143
	s_addc_u32 s3, s3, 0
	v_lshlrev_b32_e32 v102, 1, v14
	v_mov_b32_e32 v103, v143
	v_lshl_add_u64 v[104:105], s[2:3], 0, v[64:65]
	v_lshl_add_u64 v[102:103], v[104:105], 0, v[102:103]
	s_waitcnt vmcnt(7)
	ds_write2_b32 v173, v70, v71 offset1:1
	ds_write2_b32 v173, v72, v73 offset0:2 offset1:3
	s_waitcnt vmcnt(6)
	ds_write2_b32 v11, v74, v75 offset1:1
	ds_write2_b32 v13, v76, v77 offset1:1
	s_waitcnt vmcnt(5)
	ds_write2_b32 v15, v78, v79 offset1:1
	ds_write2_b32 v33, v80, v81 offset1:1
	s_waitcnt vmcnt(4)
	ds_write2_b32 v47, v82, v83 offset1:1
	ds_write2_b32 v49, v84, v85 offset1:1
	s_waitcnt vmcnt(3)
	ds_write2_b32 v51, v86, v87 offset1:1
	ds_write2_b32 v53, v88, v89 offset1:1
	s_waitcnt vmcnt(2)
	ds_write2_b32 v55, v90, v91 offset1:1
	ds_write2_b32 v57, v92, v93 offset1:1
	s_waitcnt vmcnt(1)
	ds_write2_b32 v59, v94, v95 offset1:1
	ds_write2_b32 v61, v96, v97 offset1:1
	s_waitcnt vmcnt(0)
	ds_write2_b32 v63, v98, v99 offset1:1
	ds_write2_b32 v67, v100, v101 offset1:1
	s_waitcnt lgkmcnt(0)
	ds_read2_b32 v[74:75], v7 offset0:33 offset1:41
	ds_read2_b32 v[76:77], v7 offset1:8
	ds_read2_b32 v[78:79], v7 offset0:66 offset1:74
	ds_read2_b32 v[80:81], v7 offset0:99 offset1:107
	ds_read2_b32 v[82:83], v7 offset0:132 offset1:140
	ds_read2_b32 v[84:85], v7 offset0:165 offset1:173
	s_waitcnt lgkmcnt(4)
	v_bfe_u32 v11, v76, 16, 1
	ds_read2_b32 v[86:87], v7 offset0:198 offset1:206
	v_bfe_u32 v13, v74, 16, 1
	v_add3_u32 v11, v76, v11, s19
	ds_read2_b32 v[88:89], v7 offset0:231 offset1:239
	s_waitcnt lgkmcnt(3)
	v_bfe_u32 v47, v82, 16, 1
	v_add3_u32 v13, v74, v13, s19
	v_lshrrev_b32_e32 v11, 16, v11
	v_and_or_b32 v70, v13, s20, v11
	v_add3_u32 v11, v82, v47, s19
	s_waitcnt lgkmcnt(2)
	v_bfe_u32 v13, v84, 16, 1
	v_lshrrev_b32_e32 v11, 16, v11
	v_add3_u32 v13, v84, v13, s19
	v_and_or_b32 v72, v13, s20, v11
	s_waitcnt lgkmcnt(1)
	v_bfe_u32 v11, v86, 16, 1
	v_add3_u32 v11, v86, v11, s19
	s_waitcnt lgkmcnt(0)
	v_bfe_u32 v13, v88, 16, 1
	v_bfe_u32 v15, v78, 16, 1
	v_lshrrev_b32_e32 v11, 16, v11
	v_add3_u32 v13, v88, v13, s19
	v_bfe_u32 v33, v80, 16, 1
	v_add3_u32 v15, v78, v15, s19
	v_and_or_b32 v73, v13, s20, v11
	v_bfe_u32 v11, v77, 16, 1
	v_add3_u32 v33, v80, v33, s19
	v_lshrrev_b32_e32 v15, 16, v15
	v_add3_u32 v11, v77, v11, s19
	v_bfe_u32 v13, v75, 16, 1
	v_and_or_b32 v71, v33, s20, v15
	v_lshl_add_u64 v[90:91], v[102:103], 0, v[24:25]
	v_lshrrev_b32_e32 v11, 16, v11
	v_add3_u32 v13, v75, v13, s19
	global_store_dwordx4 v[90:91], v[70:73], off
	ds_read2_b32 v[74:75], v7 offset0:16 offset1:24
	v_lshl_add_u64 v[76:77], v[102:103], 0, v[26:27]
	v_and_or_b32 v70, v13, s20, v11
	v_bfe_u32 v11, v79, 16, 1
	v_add3_u32 v11, v79, v11, s19
	v_bfe_u32 v13, v81, 16, 1
	v_lshrrev_b32_e32 v11, 16, v11
	v_add3_u32 v13, v81, v13, s19
	v_and_or_b32 v71, v13, s20, v11
	v_bfe_u32 v11, v83, 16, 1
	v_add3_u32 v11, v83, v11, s19
	v_bfe_u32 v13, v85, 16, 1
	v_lshrrev_b32_e32 v11, 16, v11
	v_add3_u32 v13, v85, v13, s19
	v_and_or_b32 v72, v13, s20, v11
	v_bfe_u32 v11, v87, 16, 1
	v_add3_u32 v11, v87, v11, s19
	v_bfe_u32 v13, v89, 16, 1
	v_lshrrev_b32_e32 v11, 16, v11
	v_add3_u32 v13, v89, v13, s19
	v_and_or_b32 v73, v13, s20, v11
	global_store_dwordx4 v[76:77], v[70:73], off
	ds_read2_b32 v[76:77], v7 offset0:49 offset1:57
	ds_read2_b32 v[78:79], v7 offset0:82 offset1:90
	ds_read2_b32 v[80:81], v7 offset0:115 offset1:123
	s_waitcnt lgkmcnt(3)
	v_bfe_u32 v11, v74, 16, 1
	v_add3_u32 v11, v74, v11, s19
	s_waitcnt lgkmcnt(2)
	v_bfe_u32 v13, v76, 16, 1
	ds_read2_b32 v[82:83], v7 offset0:148 offset1:156
	v_lshrrev_b32_e32 v11, 16, v11
	v_add3_u32 v13, v76, v13, s19
	ds_read2_b32 v[84:85], v7 offset0:181 offset1:189
	v_and_or_b32 v70, v13, s20, v11
	s_waitcnt lgkmcnt(3)
	v_bfe_u32 v11, v78, 16, 1
	v_add3_u32 v11, v78, v11, s19
	s_waitcnt lgkmcnt(2)
	v_bfe_u32 v13, v80, 16, 1
	ds_read2_b32 v[86:87], v7 offset0:214 offset1:222
	v_lshrrev_b32_e32 v11, 16, v11
	v_add3_u32 v13, v80, v13, s19
	ds_read2_b32 v[88:89], v7 offset0:247 offset1:255
	v_and_or_b32 v71, v13, s20, v11
	s_waitcnt lgkmcnt(3)
	v_bfe_u32 v11, v82, 16, 1
	v_add3_u32 v11, v82, v11, s19
	s_waitcnt lgkmcnt(2)
	v_bfe_u32 v13, v84, 16, 1
	v_lshrrev_b32_e32 v11, 16, v11
	v_add3_u32 v13, v84, v13, s19
	v_and_or_b32 v72, v13, s20, v11
	s_waitcnt lgkmcnt(1)
	v_bfe_u32 v11, v86, 16, 1
	v_add3_u32 v11, v86, v11, s19
	s_waitcnt lgkmcnt(0)
	v_bfe_u32 v13, v88, 16, 1
	v_lshrrev_b32_e32 v11, 16, v11
	v_add3_u32 v13, v88, v13, s19
	v_and_or_b32 v73, v13, s20, v11
	v_bfe_u32 v11, v75, 16, 1
	v_add3_u32 v11, v75, v11, s19
	v_bfe_u32 v13, v77, 16, 1
	v_lshl_add_u64 v[90:91], v[102:103], 0, v[28:29]
	v_lshrrev_b32_e32 v11, 16, v11
	v_add3_u32 v13, v77, v13, s19
	global_store_dwordx4 v[90:91], v[70:73], off
	v_lshl_add_u64 v[74:75], v[102:103], 0, v[30:31]
	s_nop 0
	v_and_or_b32 v70, v13, s20, v11
	v_bfe_u32 v11, v79, 16, 1
	v_add3_u32 v11, v79, v11, s19
	v_bfe_u32 v13, v81, 16, 1
	v_lshrrev_b32_e32 v11, 16, v11
	v_add3_u32 v13, v81, v13, s19
	v_and_or_b32 v71, v13, s20, v11
	v_bfe_u32 v11, v83, 16, 1
	v_add3_u32 v11, v83, v11, s19
	v_bfe_u32 v13, v85, 16, 1
	v_lshrrev_b32_e32 v11, 16, v11
	v_add3_u32 v13, v85, v13, s19
	v_and_or_b32 v72, v13, s20, v11
	v_bfe_u32 v11, v87, 16, 1
	v_add3_u32 v11, v87, v11, s19
	v_bfe_u32 v13, v89, 16, 1
	v_lshrrev_b32_e32 v11, 16, v11
	v_add3_u32 v13, v89, v13, s19
	v_and_or_b32 v73, v13, s20, v11
	global_store_dwordx4 v[74:75], v[70:73], off
	s_waitcnt lgkmcnt(0)

.LBB0_167:
	s_andn2_b64 vcc, exec, s[2:3]
	s_cbranch_vccnz .LBB0_169
	s_add_i32 s36, s31, s78
	s_cmp_gt_u32 s36, 0x85ff
	s_cbranch_scc1 .Lk_DN_single
	s_add_i32 s0, s31, 0xffffd000
	s_lshr_b32 s0, s0, 1
	v_readlane_b32 s40, v254, 0
	s_and_b32 s0, s0, 0x7fffffc0
	v_readlane_b32 s41, v254, 1
	v_readlane_b32 s42, v254, 2
	v_readlane_b32 s43, v254, 3
	v_readlane_b32 s44, v254, 4
	v_readlane_b32 s45, v254, 5
	s_and_b32 s4, s31, 0x7f
	s_lshl_b64 s[2:3], s[0:1], 14
	v_readlane_b32 s46, v254, 6
	v_readlane_b32 s47, v254, 7
	s_mov_b64 s[40:41], s[44:45]
	s_add_u32 s2, s40, s2
	s_addc_u32 s3, s41, s3
	s_lshl_b32 s5, s4, 7
	s_add_u32 s2, s2, s5
	s_addc_u32 s3, s3, 0
	v_lshl_add_u64 v[70:71], s[2:3], 0, v[142:143]
	v_lshlrev_b32_e32 v72, 2, v32
	v_mov_b32_e32 v73, v143
	v_lshl_add_u64 v[98:99], v[70:71], 0, v[72:73]
	v_add_co_u32_e32 v74, vcc, s22, v98
	v_add_u32_e32 v11, 0x420, v173
	s_nop 0
	v_addc_co_u32_e32 v75, vcc, 0, v99, vcc
	v_add_co_u32_e32 v78, vcc, s23, v98
	global_load_dwordx4 v[70:73], v[98:99], off
	s_nop 0
	global_load_dwordx4 v[74:77], v[74:75], off
	v_addc_co_u32_e32 v79, vcc, 0, v99, vcc
	v_add_co_u32_e32 v82, vcc, s24, v98
	v_add_u32_e32 v13, 0x428, v173
	s_nop 0
	v_addc_co_u32_e32 v83, vcc, 0, v99, vcc
	v_add_co_u32_e32 v86, vcc, s25, v98
	global_load_dwordx4 v[78:81], v[78:79], off
	s_nop 0
	global_load_dwordx4 v[82:85], v[82:83], off
	v_addc_co_u32_e32 v87, vcc, 0, v99, vcc
	v_add_co_u32_e32 v90, vcc, s26, v98
	v_add_u32_e32 v15, 0x840, v173
	s_nop 0
	v_addc_co_u32_e32 v91, vcc, 0, v99, vcc
	global_load_dwordx4 v[86:89], v[86:87], off
	s_nop 0
	global_load_dwordx4 v[90:93], v[90:91], off
	v_add_co_u32_e32 v94, vcc, s27, v98
	v_add_u32_e32 v33, 0x848, v173
	s_nop 0
	v_addc_co_u32_e32 v95, vcc, 0, v99, vcc
	global_load_dwordx4 v[94:97], v[94:95], off
	v_add_co_u32_e32 v98, vcc, s28, v98
	v_add_u32_e32 v47, 0xc60, v173
	s_nop 0
	v_addc_co_u32_e32 v99, vcc, 0, v99, vcc
	global_load_dwordx4 v[98:101], v[98:99], off
	s_add_i32 s31, s31, s78
	s_add_i32 s16, s16, s37
	s_add_i32 s17, s17, s18
	s_mov_b32 s69, 0
	s_add_i32 s68, s31, 0xffffd000
	s_lshr_b32 s68, s68, 1
	v_readlane_b32 s82, v254, 0
	s_and_b32 s68, s68, 0x7fffffc0
	v_readlane_b32 s83, v254, 1
	v_readlane_b32 s84, v254, 2
	v_readlane_b32 s85, v254, 3
	v_readlane_b32 s86, v254, 4
	v_readlane_b32 s87, v254, 5
	s_and_b32 s72, s31, 0x7f
	s_lshl_b64 s[70:71], s[68:69], 14
	v_readlane_b32 s90, v254, 6
	v_readlane_b32 s91, v254, 7
	s_mov_b64 s[82:83], s[86:87]
	s_add_u32 s70, s82, s70
	s_addc_u32 s71, s83, s71
	s_lshl_b32 s73, s72, 7
	s_add_u32 s70, s70, s73
	s_addc_u32 s71, s71, 0
	v_lshl_add_u64 v[220:221], s[70:71], 0, v[142:143]
	v_lshlrev_b32_e32 v222, 2, v32
	v_mov_b32_e32 v223, v143
	v_lshl_add_u64 v[248:249], v[220:221], 0, v[222:223]
	v_add_co_u32_e32 v224, vcc, s22, v248
	v_add_u32_e32 v11, 0x420, v173
	s_nop 0
	v_addc_co_u32_e32 v225, vcc, 0, v249, vcc
	v_add_co_u32_e32 v228, vcc, s23, v248
	global_load_dwordx4 v[220:223], v[248:249], off
	s_nop 0
	global_load_dwordx4 v[224:227], v[224:225], off
	v_addc_co_u32_e32 v229, vcc, 0, v249, vcc
	v_add_co_u32_e32 v232, vcc, s24, v248
	v_add_u32_e32 v13, 0x428, v173
	s_nop 0
	v_addc_co_u32_e32 v233, vcc, 0, v249, vcc
	v_add_co_u32_e32 v236, vcc, s25, v248
	global_load_dwordx4 v[228:231], v[228:229], off
	s_nop 0
	global_load_dwordx4 v[232:235], v[232:233], off
	v_addc_co_u32_e32 v237, vcc, 0, v249, vcc
	v_add_co_u32_e32 v240, vcc, s26, v248
	v_add_u32_e32 v15, 0x840, v173
	s_nop 0
	v_addc_co_u32_e32 v241, vcc, 0, v249, vcc
	global_load_dwordx4 v[236:239], v[236:237], off
	s_nop 0
	global_load_dwordx4 v[240:243], v[240:241], off
	v_add_co_u32_e32 v244, vcc, s27, v248
	v_add_u32_e32 v33, 0x848, v173
	s_nop 0
	v_addc_co_u32_e32 v245, vcc, 0, v249, vcc
	global_load_dwordx4 v[244:247], v[244:245], off
	v_add_co_u32_e32 v248, vcc, s28, v248
	v_add_u32_e32 v47, 0xc60, v173
	s_nop 0
	v_addc_co_u32_e32 v249, vcc, 0, v249, vcc
	global_load_dwordx4 v[248:251], v[248:249], off
	s_sub_i32 s31, s31, s78
	s_sub_i32 s16, s16, s37
	s_sub_i32 s17, s17, s18
	v_add_u32_e32 v49, 0xc68, v173
	v_add_u32_e32 v51, 0x1080, v173
	v_add_u32_e32 v53, 0x1088, v173
	v_add_u32_e32 v55, 0x14a0, v173
	v_add_u32_e32 v57, 0x14a8, v173
	v_add_u32_e32 v59, 0x18c0, v173
	v_add_u32_e32 v61, 0x18c8, v173
	v_add_u32_e32 v63, 0x1ce0, v173
	v_add_u32_e32 v65, 0x1ce8, v173
	v_mov_b32_e32 v102, v143
	v_mov_b32_e32 v103, v143
	v_mov_b32_e32 v104, v143
	v_mov_b32_e32 v105, v143
	s_mul_i32 s4, s4, 0x56000
	s_add_u32 s2, s8, s4
	s_addc_u32 s3, s9, 0
	s_add_u32 s2, s2, s0
	s_addc_u32 s3, s3, 0
	v_lshl_add_u64 v[106:107], s[2:3], 0, v[144:145]
	v_lshl_add_u64 v[106:107], v[106:107], 0, v[34:35]
	s_mov_b64 s[42:43], s[46:47]
	s_waitcnt vmcnt(15)
	ds_write2_b32 v173, v70, v71 offset1:1
	ds_write2_b32 v173, v72, v73 offset0:2 offset1:3
	s_waitcnt vmcnt(14)
	ds_write2_b32 v11, v74, v75 offset1:1
	ds_write2_b32 v13, v76, v77 offset1:1
	s_waitcnt vmcnt(13)
	ds_write2_b32 v15, v78, v79 offset1:1
	ds_write2_b32 v33, v80, v81 offset1:1
	s_waitcnt vmcnt(12)
	ds_write2_b32 v47, v82, v83 offset1:1
	ds_write2_b32 v49, v84, v85 offset1:1
	s_waitcnt vmcnt(11)
	ds_write2_b32 v51, v86, v87 offset1:1
	ds_write2_b32 v53, v88, v89 offset1:1
	s_waitcnt vmcnt(10)
	ds_write2_b32 v55, v90, v91 offset1:1
	ds_write2_b32 v57, v92, v93 offset1:1
	s_waitcnt vmcnt(9)
	ds_write2_b32 v59, v94, v95 offset1:1
	ds_write2_b32 v61, v96, v97 offset1:1
	s_waitcnt vmcnt(8)
	ds_write2_b32 v63, v98, v99 offset1:1
	ds_write2_b32 v65, v100, v101 offset1:1
	s_waitcnt lgkmcnt(0)
	ds_read2_b32 v[70:71], v149 offset1:16
	ds_read2_b32 v[72:73], v149 offset0:33 offset1:49
	ds_read2_b32 v[74:75], v149 offset0:66 offset1:82
	ds_read2_b32 v[76:77], v149 offset0:99 offset1:115
	ds_read2_b32 v[78:79], v149 offset0:132 offset1:148
	ds_read2_b32 v[80:81], v149 offset0:165 offset1:181
	ds_read2_b32 v[82:83], v149 offset0:198 offset1:214
	ds_read2_b32 v[84:85], v149 offset0:231 offset1:247
	s_waitcnt lgkmcnt(7)
	v_mul_f32_e32 v11, 0x44000000, v70
	s_waitcnt lgkmcnt(6)
	v_mul_f32_e32 v13, 0x44000000, v72
	v_med3_f32 v11, v11, s29, v9
	v_med3_f32 v13, v13, s29, v9
	v_cvt_pk_fp8_f32 v102, v11, v13
	s_waitcnt lgkmcnt(5)
	v_mul_f32_e32 v15, 0x44000000, v74
	s_waitcnt lgkmcnt(4)
	v_mul_f32_e32 v33, 0x44000000, v76
	v_med3_f32 v13, v15, s29, v9
	v_med3_f32 v15, v33, s29, v9
	s_waitcnt lgkmcnt(3)
	v_mul_f32_e32 v11, 0x44000000, v78
	v_cvt_pk_fp8_f32 v102, v13, v15 op_sel:[0,0,1]
	s_waitcnt lgkmcnt(2)
	v_mul_f32_e32 v13, 0x44000000, v80
	v_med3_f32 v11, v11, s29, v9
	v_med3_f32 v13, v13, s29, v9
	v_cvt_pk_fp8_f32 v103, v11, v13
	v_add_u32_e32 v11, 0x400, v149
	ds_read2_b32 v[86:87], v11 offset0:8 offset1:24
	ds_read2_b32 v[88:89], v11 offset0:41 offset1:57
	ds_read2_b32 v[90:91], v11 offset0:74 offset1:90
	ds_read2_b32 v[92:93], v11 offset0:107 offset1:123
	s_waitcnt lgkmcnt(5)
	v_mul_f32_e32 v15, 0x44000000, v82
	s_waitcnt lgkmcnt(4)
	v_mul_f32_e32 v33, 0x44000000, v84
	v_med3_f32 v15, v15, s29, v9
	v_med3_f32 v33, v33, s29, v9
	v_cvt_pk_fp8_f32 v103, v15, v33 op_sel:[0,0,1]
	s_waitcnt lgkmcnt(3)
	v_mul_f32_e32 v13, 0x44000000, v86
	s_waitcnt lgkmcnt(2)
	v_mul_f32_e32 v15, 0x44000000, v88
	v_med3_f32 v13, v13, s29, v9
	v_med3_f32 v15, v15, s29, v9
	v_cvt_pk_fp8_f32 v104, v13, v15
	ds_read2_b32 v[94:95], v11 offset0:140 offset1:156
	ds_read2_b32 v[96:97], v11 offset0:173 offset1:189
	ds_read2_b32 v[98:99], v11 offset0:206 offset1:222
	s_waitcnt lgkmcnt(4)
	v_mul_f32_e32 v33, 0x44000000, v90
	s_waitcnt lgkmcnt(3)
	v_mul_f32_e32 v47, 0x44000000, v92
	v_med3_f32 v33, v33, s29, v9
	v_med3_f32 v13, v47, s29, v9
	ds_read2_b32 v[100:101], v11 offset0:239 offset1:255
	v_cvt_pk_fp8_f32 v104, v33, v13 op_sel:[0,0,1]
	s_waitcnt lgkmcnt(3)
	v_mul_f32_e32 v13, 0x44000000, v94
	s_waitcnt lgkmcnt(2)
	v_mul_f32_e32 v15, 0x44000000, v96
	v_med3_f32 v11, v13, s29, v9
	v_med3_f32 v13, v15, s29, v9
	v_cvt_pk_fp8_f32 v105, v11, v13
	s_waitcnt lgkmcnt(1)
	v_mul_f32_e32 v33, 0x44000000, v98
	s_waitcnt lgkmcnt(0)
	v_mul_f32_e32 v11, 0x44000000, v100
	v_med3_f32 v13, v33, s29, v9
	v_med3_f32 v11, v11, s29, v9
	v_cvt_pk_fp8_f32 v105, v13, v11 op_sel:[0,0,1]
	v_mul_f32_e32 v11, 0x44000000, v71
	v_mul_f32_e32 v13, 0x44000000, v73
	v_med3_f32 v11, v11, s29, v9
	v_med3_f32 v13, v13, s29, v9
	v_mov_b32_e32 v70, v143
	v_cvt_pk_fp8_f32 v70, v11, v13
	v_mul_f32_e32 v15, 0x44000000, v75
	v_mul_f32_e32 v11, 0x44000000, v77
	v_med3_f32 v13, v15, s29, v9
	v_med3_f32 v11, v11, s29, v9
	v_cvt_pk_fp8_f32 v70, v13, v11 op_sel:[0,0,1]
	v_mul_f32_e32 v11, 0x44000000, v79
	v_mul_f32_e32 v13, 0x44000000, v81
	v_med3_f32 v11, v11, s29, v9
	v_med3_f32 v13, v13, s29, v9
	v_mov_b32_e32 v71, v143
	v_cvt_pk_fp8_f32 v71, v11, v13
	v_mul_f32_e32 v15, 0x44000000, v83
	v_mul_f32_e32 v11, 0x44000000, v85
	v_med3_f32 v13, v15, s29, v9
	v_med3_f32 v11, v11, s29, v9
	v_cvt_pk_fp8_f32 v71, v13, v11 op_sel:[0,0,1]
	v_mul_f32_e32 v11, 0x44000000, v87
	v_mul_f32_e32 v13, 0x44000000, v89
	v_med3_f32 v11, v11, s29, v9
	v_med3_f32 v13, v13, s29, v9
	v_mov_b32_e32 v72, v143
	v_cvt_pk_fp8_f32 v72, v11, v13
	v_mul_f32_e32 v15, 0x44000000, v91
	v_mul_f32_e32 v11, 0x44000000, v93
	v_med3_f32 v13, v15, s29, v9
	v_med3_f32 v11, v11, s29, v9
	v_cvt_pk_fp8_f32 v72, v13, v11 op_sel:[0,0,1]
	v_mul_f32_e32 v11, 0x44000000, v95
	v_mul_f32_e32 v13, 0x44000000, v97
	v_med3_f32 v11, v11, s29, v9
	v_med3_f32 v13, v13, s29, v9
	v_mov_b32_e32 v73, v143
	v_cvt_pk_fp8_f32 v73, v11, v13
	v_mul_f32_e32 v15, 0x44000000, v99
	v_mul_f32_e32 v11, 0x44000000, v101
	v_med3_f32 v13, v15, s29, v9
	v_med3_f32 v11, v11, s29, v9
	v_cvt_pk_fp8_f32 v73, v13, v11 op_sel:[0,0,1]
	v_add_co_u32_e32 v74, vcc, 0x2b000, v106
	global_store_dwordx4 v[106:107], v[102:105], off
	s_nop 0
	v_addc_co_u32_e32 v75, vcc, 0, v107, vcc
	global_store_dwordx4 v[74:75], v[70:73], off
	s_waitcnt lgkmcnt(0)
	s_add_i32 s31, s31, s78
	s_add_i32 s16, s16, s37
	s_add_i32 s17, s17, s18
	s_add_i32 s0, s31, 0xffffd000
	s_lshr_b32 s0, s0, 1
	v_readlane_b32 s40, v254, 0
	s_and_b32 s0, s0, 0x7fffffc0
	v_readlane_b32 s41, v254, 1
	v_readlane_b32 s42, v254, 2
	v_readlane_b32 s43, v254, 3
	v_readlane_b32 s44, v254, 4
	v_readlane_b32 s45, v254, 5
	s_and_b32 s4, s31, 0x7f
	s_lshl_b64 s[2:3], s[0:1], 14
	v_readlane_b32 s46, v254, 6
	v_readlane_b32 s47, v254, 7
	s_mov_b64 s[40:41], s[44:45]
	s_add_u32 s2, s40, s2
	s_addc_u32 s3, s41, s3
	s_lshl_b32 s5, s4, 7
	s_add_u32 s2, s2, s5
	s_addc_u32 s3, s3, 0
	v_lshl_add_u64 v[70:71], s[2:3], 0, v[142:143]
	v_lshlrev_b32_e32 v72, 2, v32
	v_mov_b32_e32 v73, v143
	v_lshl_add_u64 v[98:99], v[70:71], 0, v[72:73]
	v_add_co_u32_e32 v74, vcc, s22, v98
	v_add_u32_e32 v11, 0x420, v173
	s_nop 0
	v_addc_co_u32_e32 v75, vcc, 0, v99, vcc
	v_add_co_u32_e32 v78, vcc, s23, v98
	s_nop 0
	v_addc_co_u32_e32 v79, vcc, 0, v99, vcc
	v_add_co_u32_e32 v82, vcc, s24, v98
	v_add_u32_e32 v13, 0x428, v173
	s_nop 0
	v_addc_co_u32_e32 v83, vcc, 0, v99, vcc
	v_add_co_u32_e32 v86, vcc, s25, v98
	s_nop 0
	v_addc_co_u32_e32 v87, vcc, 0, v99, vcc
	v_add_co_u32_e32 v90, vcc, s26, v98
	v_add_u32_e32 v15, 0x840, v173
	s_nop 0
	v_addc_co_u32_e32 v91, vcc, 0, v99, vcc
	s_nop 0
	v_add_co_u32_e32 v94, vcc, s27, v98
	v_add_u32_e32 v33, 0x848, v173
	s_nop 0
	v_addc_co_u32_e32 v95, vcc, 0, v99, vcc
	v_add_co_u32_e32 v98, vcc, s28, v98
	v_add_u32_e32 v47, 0xc60, v173
	s_nop 0
	v_addc_co_u32_e32 v99, vcc, 0, v99, vcc
	v_add_u32_e32 v49, 0xc68, v173
	v_add_u32_e32 v51, 0x1080, v173
	v_add_u32_e32 v53, 0x1088, v173
	v_add_u32_e32 v55, 0x14a0, v173
	v_add_u32_e32 v57, 0x14a8, v173
	v_add_u32_e32 v59, 0x18c0, v173
	v_add_u32_e32 v61, 0x18c8, v173
	v_add_u32_e32 v63, 0x1ce0, v173
	v_add_u32_e32 v65, 0x1ce8, v173
	v_mov_b32_e32 v102, v143
	v_mov_b32_e32 v103, v143
	v_mov_b32_e32 v104, v143
	v_mov_b32_e32 v105, v143
	s_mul_i32 s4, s4, 0x56000
	s_add_u32 s2, s8, s4
	s_addc_u32 s3, s9, 0
	s_add_u32 s2, s2, s0
	s_addc_u32 s3, s3, 0
	v_lshl_add_u64 v[106:107], s[2:3], 0, v[144:145]
	v_lshl_add_u64 v[106:107], v[106:107], 0, v[34:35]
	s_mov_b64 s[42:43], s[46:47]
	s_waitcnt vmcnt(9)
	ds_write2_b32 v173, v220, v221 offset1:1
	ds_write2_b32 v173, v222, v223 offset0:2 offset1:3
	s_waitcnt vmcnt(8)
	ds_write2_b32 v11, v224, v225 offset1:1
	ds_write2_b32 v13, v226, v227 offset1:1
	s_waitcnt vmcnt(7)
	ds_write2_b32 v15, v228, v229 offset1:1
	ds_write2_b32 v33, v230, v231 offset1:1
	s_waitcnt vmcnt(6)
	ds_write2_b32 v47, v232, v233 offset1:1
	ds_write2_b32 v49, v234, v235 offset1:1
	s_waitcnt vmcnt(5)
	ds_write2_b32 v51, v236, v237 offset1:1
	ds_write2_b32 v53, v238, v239 offset1:1
	s_waitcnt vmcnt(4)
	ds_write2_b32 v55, v240, v241 offset1:1
	ds_write2_b32 v57, v242, v243 offset1:1
	s_waitcnt vmcnt(3)
	ds_write2_b32 v59, v244, v245 offset1:1
	ds_write2_b32 v61, v246, v247 offset1:1
	s_waitcnt vmcnt(2)
	ds_write2_b32 v63, v248, v249 offset1:1
	ds_write2_b32 v65, v250, v251 offset1:1
	s_waitcnt lgkmcnt(0)
	ds_read2_b32 v[70:71], v149 offset1:16
	ds_read2_b32 v[72:73], v149 offset0:33 offset1:49
	ds_read2_b32 v[74:75], v149 offset0:66 offset1:82
	ds_read2_b32 v[76:77], v149 offset0:99 offset1:115
	ds_read2_b32 v[78:79], v149 offset0:132 offset1:148
	ds_read2_b32 v[80:81], v149 offset0:165 offset1:181
	ds_read2_b32 v[82:83], v149 offset0:198 offset1:214
	ds_read2_b32 v[84:85], v149 offset0:231 offset1:247
	s_waitcnt lgkmcnt(7)
	v_mul_f32_e32 v11, 0x44000000, v70
	s_waitcnt lgkmcnt(6)
	v_mul_f32_e32 v13, 0x44000000, v72
	v_med3_f32 v11, v11, s29, v9
	v_med3_f32 v13, v13, s29, v9
	v_cvt_pk_fp8_f32 v102, v11, v13
	s_waitcnt lgkmcnt(5)
	v_mul_f32_e32 v15, 0x44000000, v74
	s_waitcnt lgkmcnt(4)
	v_mul_f32_e32 v33, 0x44000000, v76
	v_med3_f32 v13, v15, s29, v9
	v_med3_f32 v15, v33, s29, v9
	s_waitcnt lgkmcnt(3)
	v_mul_f32_e32 v11, 0x44000000, v78
	v_cvt_pk_fp8_f32 v102, v13, v15 op_sel:[0,0,1]
	s_waitcnt lgkmcnt(2)
	v_mul_f32_e32 v13, 0x44000000, v80
	v_med3_f32 v11, v11, s29, v9
	v_med3_f32 v13, v13, s29, v9
	v_cvt_pk_fp8_f32 v103, v11, v13
	v_add_u32_e32 v11, 0x400, v149
	ds_read2_b32 v[86:87], v11 offset0:8 offset1:24
	ds_read2_b32 v[88:89], v11 offset0:41 offset1:57
	ds_read2_b32 v[90:91], v11 offset0:74 offset1:90
	ds_read2_b32 v[92:93], v11 offset0:107 offset1:123
	s_waitcnt lgkmcnt(5)
	v_mul_f32_e32 v15, 0x44000000, v82
	s_waitcnt lgkmcnt(4)
	v_mul_f32_e32 v33, 0x44000000, v84
	v_med3_f32 v15, v15, s29, v9
	v_med3_f32 v33, v33, s29, v9
	v_cvt_pk_fp8_f32 v103, v15, v33 op_sel:[0,0,1]
	s_waitcnt lgkmcnt(3)
	v_mul_f32_e32 v13, 0x44000000, v86
	s_waitcnt lgkmcnt(2)
	v_mul_f32_e32 v15, 0x44000000, v88
	v_med3_f32 v13, v13, s29, v9
	v_med3_f32 v15, v15, s29, v9
	v_cvt_pk_fp8_f32 v104, v13, v15
	ds_read2_b32 v[94:95], v11 offset0:140 offset1:156
	ds_read2_b32 v[96:97], v11 offset0:173 offset1:189
	ds_read2_b32 v[98:99], v11 offset0:206 offset1:222
	s_waitcnt lgkmcnt(4)
	v_mul_f32_e32 v33, 0x44000000, v90
	s_waitcnt lgkmcnt(3)
	v_mul_f32_e32 v47, 0x44000000, v92
	v_med3_f32 v33, v33, s29, v9
	v_med3_f32 v13, v47, s29, v9
	ds_read2_b32 v[100:101], v11 offset0:239 offset1:255
	v_cvt_pk_fp8_f32 v104, v33, v13 op_sel:[0,0,1]
	s_waitcnt lgkmcnt(3)
	v_mul_f32_e32 v13, 0x44000000, v94
	s_waitcnt lgkmcnt(2)
	v_mul_f32_e32 v15, 0x44000000, v96
	v_med3_f32 v11, v13, s29, v9
	v_med3_f32 v13, v15, s29, v9
	v_cvt_pk_fp8_f32 v105, v11, v13
	s_waitcnt lgkmcnt(1)
	v_mul_f32_e32 v33, 0x44000000, v98
	s_waitcnt lgkmcnt(0)
	v_mul_f32_e32 v11, 0x44000000, v100
	v_med3_f32 v13, v33, s29, v9
	v_med3_f32 v11, v11, s29, v9
	v_cvt_pk_fp8_f32 v105, v13, v11 op_sel:[0,0,1]
	v_mul_f32_e32 v11, 0x44000000, v71
	v_mul_f32_e32 v13, 0x44000000, v73
	v_med3_f32 v11, v11, s29, v9
	v_med3_f32 v13, v13, s29, v9
	v_mov_b32_e32 v70, v143
	v_cvt_pk_fp8_f32 v70, v11, v13
	v_mul_f32_e32 v15, 0x44000000, v75
	v_mul_f32_e32 v11, 0x44000000, v77
	v_med3_f32 v13, v15, s29, v9
	v_med3_f32 v11, v11, s29, v9
	v_cvt_pk_fp8_f32 v70, v13, v11 op_sel:[0,0,1]
	v_mul_f32_e32 v11, 0x44000000, v79
	v_mul_f32_e32 v13, 0x44000000, v81
	v_med3_f32 v11, v11, s29, v9
	v_med3_f32 v13, v13, s29, v9
	v_mov_b32_e32 v71, v143
	v_cvt_pk_fp8_f32 v71, v11, v13
	v_mul_f32_e32 v15, 0x44000000, v83
	v_mul_f32_e32 v11, 0x44000000, v85
	v_med3_f32 v13, v15, s29, v9
	v_med3_f32 v11, v11, s29, v9
	v_cvt_pk_fp8_f32 v71, v13, v11 op_sel:[0,0,1]
	v_mul_f32_e32 v11, 0x44000000, v87
	v_mul_f32_e32 v13, 0x44000000, v89
	v_med3_f32 v11, v11, s29, v9
	v_med3_f32 v13, v13, s29, v9
	v_mov_b32_e32 v72, v143
	v_cvt_pk_fp8_f32 v72, v11, v13
	v_mul_f32_e32 v15, 0x44000000, v91
	v_mul_f32_e32 v11, 0x44000000, v93
	v_med3_f32 v13, v15, s29, v9
	v_med3_f32 v11, v11, s29, v9
	v_cvt_pk_fp8_f32 v72, v13, v11 op_sel:[0,0,1]
	v_mul_f32_e32 v11, 0x44000000, v95
	v_mul_f32_e32 v13, 0x44000000, v97
	v_med3_f32 v11, v11, s29, v9
	v_med3_f32 v13, v13, s29, v9
	v_mov_b32_e32 v73, v143
	v_cvt_pk_fp8_f32 v73, v11, v13
	v_mul_f32_e32 v15, 0x44000000, v99
	v_mul_f32_e32 v11, 0x44000000, v101
	v_med3_f32 v13, v15, s29, v9
	v_med3_f32 v11, v11, s29, v9
	v_cvt_pk_fp8_f32 v73, v13, v11 op_sel:[0,0,1]
	v_add_co_u32_e32 v74, vcc, 0x2b000, v106
	global_store_dwordx4 v[106:107], v[102:105], off
	s_nop 0
	v_addc_co_u32_e32 v75, vcc, 0, v107, vcc
	global_store_dwordx4 v[74:75], v[70:73], off
	s_waitcnt lgkmcnt(0)
	s_branch .LBB0_169
.Lk_DN_single:
	s_add_i32 s0, s31, 0xffffd000
	s_lshr_b32 s0, s0, 1
	v_readlane_b32 s40, v254, 0
	s_and_b32 s0, s0, 0x7fffffc0
	v_readlane_b32 s41, v254, 1
	v_readlane_b32 s42, v254, 2
	v_readlane_b32 s43, v254, 3
	v_readlane_b32 s44, v254, 4
	v_readlane_b32 s45, v254, 5
	s_and_b32 s4, s31, 0x7f
	s_lshl_b64 s[2:3], s[0:1], 14
	v_readlane_b32 s46, v254, 6
	v_readlane_b32 s47, v254, 7
	s_mov_b64 s[40:41], s[44:45]
	s_add_u32 s2, s40, s2
	s_addc_u32 s3, s41, s3
	s_lshl_b32 s5, s4, 7
	s_add_u32 s2, s2, s5
	s_addc_u32 s3, s3, 0
	v_lshl_add_u64 v[70:71], s[2:3], 0, v[142:143]
	v_lshlrev_b32_e32 v72, 2, v32
	v_mov_b32_e32 v73, v143
	v_lshl_add_u64 v[98:99], v[70:71], 0, v[72:73]
	v_add_co_u32_e32 v74, vcc, s22, v98
	v_add_u32_e32 v11, 0x420, v173
	s_nop 0
	v_addc_co_u32_e32 v75, vcc, 0, v99, vcc
	v_add_co_u32_e32 v78, vcc, s23, v98
	global_load_dwordx4 v[70:73], v[98:99], off
	s_nop 0
	global_load_dwordx4 v[74:77], v[74:75], off
	v_addc_co_u32_e32 v79, vcc, 0, v99, vcc
	v_add_co_u32_e32 v82, vcc, s24, v98
	v_add_u32_e32 v13, 0x428, v173
	s_nop 0
	v_addc_co_u32_e32 v83, vcc, 0, v99, vcc
	v_add_co_u32_e32 v86, vcc, s25, v98
	global_load_dwordx4 v[78:81], v[78:79], off
	s_nop 0
	global_load_dwordx4 v[82:85], v[82:83], off
	v_addc_co_u32_e32 v87, vcc, 0, v99, vcc
	v_add_co_u32_e32 v90, vcc, s26, v98
	v_add_u32_e32 v15, 0x840, v173
	s_nop 0
	v_addc_co_u32_e32 v91, vcc, 0, v99, vcc
	global_load_dwordx4 v[86:89], v[86:87], off
	s_nop 0
	global_load_dwordx4 v[90:93], v[90:91], off
	v_add_co_u32_e32 v94, vcc, s27, v98
	v_add_u32_e32 v33, 0x848, v173
	s_nop 0
	v_addc_co_u32_e32 v95, vcc, 0, v99, vcc
	global_load_dwordx4 v[94:97], v[94:95], off
	v_add_co_u32_e32 v98, vcc, s28, v98
	v_add_u32_e32 v47, 0xc60, v173
	s_nop 0
	v_addc_co_u32_e32 v99, vcc, 0, v99, vcc
	global_load_dwordx4 v[98:101], v[98:99], off
	v_add_u32_e32 v49, 0xc68, v173
	v_add_u32_e32 v51, 0x1080, v173
	v_add_u32_e32 v53, 0x1088, v173
	v_add_u32_e32 v55, 0x14a0, v173
	v_add_u32_e32 v57, 0x14a8, v173
	v_add_u32_e32 v59, 0x18c0, v173
	v_add_u32_e32 v61, 0x18c8, v173
	v_add_u32_e32 v63, 0x1ce0, v173
	v_add_u32_e32 v65, 0x1ce8, v173
	v_mov_b32_e32 v102, v143
	v_mov_b32_e32 v103, v143
	v_mov_b32_e32 v104, v143
	v_mov_b32_e32 v105, v143
	s_mul_i32 s4, s4, 0x56000
	s_add_u32 s2, s8, s4
	s_addc_u32 s3, s9, 0
	s_add_u32 s2, s2, s0
	s_addc_u32 s3, s3, 0
	v_lshl_add_u64 v[106:107], s[2:3], 0, v[144:145]
	v_lshl_add_u64 v[106:107], v[106:107], 0, v[34:35]
	s_mov_b64 s[42:43], s[46:47]
	s_waitcnt vmcnt(7)
	ds_write2_b32 v173, v70, v71 offset1:1
	ds_write2_b32 v173, v72, v73 offset0:2 offset1:3
	s_waitcnt vmcnt(6)
	ds_write2_b32 v11, v74, v75 offset1:1
	ds_write2_b32 v13, v76, v77 offset1:1
	s_waitcnt vmcnt(5)
	ds_write2_b32 v15, v78, v79 offset1:1
	ds_write2_b32 v33, v80, v81 offset1:1
	s_waitcnt vmcnt(4)
	ds_write2_b32 v47, v82, v83 offset1:1
	ds_write2_b32 v49, v84, v85 offset1:1
	s_waitcnt vmcnt(3)
	ds_write2_b32 v51, v86, v87 offset1:1
	ds_write2_b32 v53, v88, v89 offset1:1
	s_waitcnt vmcnt(2)
	ds_write2_b32 v55, v90, v91 offset1:1
	ds_write2_b32 v57, v92, v93 offset1:1
	s_waitcnt vmcnt(1)
	ds_write2_b32 v59, v94, v95 offset1:1
	ds_write2_b32 v61, v96, v97 offset1:1
	s_waitcnt vmcnt(0)
	ds_write2_b32 v63, v98, v99 offset1:1
	ds_write2_b32 v65, v100, v101 offset1:1
	s_waitcnt lgkmcnt(0)
	ds_read2_b32 v[70:71], v149 offset1:16
	ds_read2_b32 v[72:73], v149 offset0:33 offset1:49
	ds_read2_b32 v[74:75], v149 offset0:66 offset1:82
	ds_read2_b32 v[76:77], v149 offset0:99 offset1:115
	ds_read2_b32 v[78:79], v149 offset0:132 offset1:148
	ds_read2_b32 v[80:81], v149 offset0:165 offset1:181
	ds_read2_b32 v[82:83], v149 offset0:198 offset1:214
	ds_read2_b32 v[84:85], v149 offset0:231 offset1:247
	s_waitcnt lgkmcnt(7)
	v_mul_f32_e32 v11, 0x44000000, v70
	s_waitcnt lgkmcnt(6)
	v_mul_f32_e32 v13, 0x44000000, v72
	v_med3_f32 v11, v11, s29, v9
	v_med3_f32 v13, v13, s29, v9
	v_cvt_pk_fp8_f32 v102, v11, v13
	s_waitcnt lgkmcnt(5)
	v_mul_f32_e32 v15, 0x44000000, v74
	s_waitcnt lgkmcnt(4)
	v_mul_f32_e32 v33, 0x44000000, v76
	v_med3_f32 v13, v15, s29, v9
	v_med3_f32 v15, v33, s29, v9
	s_waitcnt lgkmcnt(3)
	v_mul_f32_e32 v11, 0x44000000, v78
	v_cvt_pk_fp8_f32 v102, v13, v15 op_sel:[0,0,1]
	s_waitcnt lgkmcnt(2)
	v_mul_f32_e32 v13, 0x44000000, v80
	v_med3_f32 v11, v11, s29, v9
	v_med3_f32 v13, v13, s29, v9
	v_cvt_pk_fp8_f32 v103, v11, v13
	v_add_u32_e32 v11, 0x400, v149
	ds_read2_b32 v[86:87], v11 offset0:8 offset1:24
	ds_read2_b32 v[88:89], v11 offset0:41 offset1:57
	ds_read2_b32 v[90:91], v11 offset0:74 offset1:90
	ds_read2_b32 v[92:93], v11 offset0:107 offset1:123
	s_waitcnt lgkmcnt(5)
	v_mul_f32_e32 v15, 0x44000000, v82
	s_waitcnt lgkmcnt(4)
	v_mul_f32_e32 v33, 0x44000000, v84
	v_med3_f32 v15, v15, s29, v9
	v_med3_f32 v33, v33, s29, v9
	v_cvt_pk_fp8_f32 v103, v15, v33 op_sel:[0,0,1]
	s_waitcnt lgkmcnt(3)
	v_mul_f32_e32 v13, 0x44000000, v86
	s_waitcnt lgkmcnt(2)
	v_mul_f32_e32 v15, 0x44000000, v88
	v_med3_f32 v13, v13, s29, v9
	v_med3_f32 v15, v15, s29, v9
	v_cvt_pk_fp8_f32 v104, v13, v15
	ds_read2_b32 v[94:95], v11 offset0:140 offset1:156
	ds_read2_b32 v[96:97], v11 offset0:173 offset1:189
	ds_read2_b32 v[98:99], v11 offset0:206 offset1:222
	s_waitcnt lgkmcnt(4)
	v_mul_f32_e32 v33, 0x44000000, v90
	s_waitcnt lgkmcnt(3)
	v_mul_f32_e32 v47, 0x44000000, v92
	v_med3_f32 v33, v33, s29, v9
	v_med3_f32 v13, v47, s29, v9
	ds_read2_b32 v[100:101], v11 offset0:239 offset1:255
	v_cvt_pk_fp8_f32 v104, v33, v13 op_sel:[0,0,1]
	s_waitcnt lgkmcnt(3)
	v_mul_f32_e32 v13, 0x44000000, v94
	s_waitcnt lgkmcnt(2)
	v_mul_f32_e32 v15, 0x44000000, v96
	v_med3_f32 v11, v13, s29, v9
	v_med3_f32 v13, v15, s29, v9
	v_cvt_pk_fp8_f32 v105, v11, v13
	s_waitcnt lgkmcnt(1)
	v_mul_f32_e32 v33, 0x44000000, v98
	s_waitcnt lgkmcnt(0)
	v_mul_f32_e32 v11, 0x44000000, v100
	v_med3_f32 v13, v33, s29, v9
	v_med3_f32 v11, v11, s29, v9
	v_cvt_pk_fp8_f32 v105, v13, v11 op_sel:[0,0,1]
	v_mul_f32_e32 v11, 0x44000000, v71
	v_mul_f32_e32 v13, 0x44000000, v73
	v_med3_f32 v11, v11, s29, v9
	v_med3_f32 v13, v13, s29, v9
	v_mov_b32_e32 v70, v143
	v_cvt_pk_fp8_f32 v70, v11, v13
	v_mul_f32_e32 v15, 0x44000000, v75
	v_mul_f32_e32 v11, 0x44000000, v77
	v_med3_f32 v13, v15, s29, v9
	v_med3_f32 v11, v11, s29, v9
	v_cvt_pk_fp8_f32 v70, v13, v11 op_sel:[0,0,1]
	v_mul_f32_e32 v11, 0x44000000, v79
	v_mul_f32_e32 v13, 0x44000000, v81
	v_med3_f32 v11, v11, s29, v9
	v_med3_f32 v13, v13, s29, v9
	v_mov_b32_e32 v71, v143
	v_cvt_pk_fp8_f32 v71, v11, v13
	v_mul_f32_e32 v15, 0x44000000, v83
	v_mul_f32_e32 v11, 0x44000000, v85
	v_med3_f32 v13, v15, s29, v9
	v_med3_f32 v11, v11, s29, v9
	v_cvt_pk_fp8_f32 v71, v13, v11 op_sel:[0,0,1]
	v_mul_f32_e32 v11, 0x44000000, v87
	v_mul_f32_e32 v13, 0x44000000, v89
	v_med3_f32 v11, v11, s29, v9
	v_med3_f32 v13, v13, s29, v9
	v_mov_b32_e32 v72, v143
	v_cvt_pk_fp8_f32 v72, v11, v13
	v_mul_f32_e32 v15, 0x44000000, v91
	v_mul_f32_e32 v11, 0x44000000, v93
	v_med3_f32 v13, v15, s29, v9
	v_med3_f32 v11, v11, s29, v9
	v_cvt_pk_fp8_f32 v72, v13, v11 op_sel:[0,0,1]
	v_mul_f32_e32 v11, 0x44000000, v95
	v_mul_f32_e32 v13, 0x44000000, v97
	v_med3_f32 v11, v11, s29, v9
	v_med3_f32 v13, v13, s29, v9
	v_mov_b32_e32 v73, v143
	v_cvt_pk_fp8_f32 v73, v11, v13
	v_mul_f32_e32 v15, 0x44000000, v99
	v_mul_f32_e32 v11, 0x44000000, v101
	v_med3_f32 v13, v15, s29, v9
	v_med3_f32 v11, v11, s29, v9
	v_cvt_pk_fp8_f32 v73, v13, v11 op_sel:[0,0,1]
	v_add_co_u32_e32 v74, vcc, 0x2b000, v106
	global_store_dwordx4 v[106:107], v[102:105], off
	s_nop 0
	v_addc_co_u32_e32 v75, vcc, 0, v107, vcc
	global_store_dwordx4 v[74:75], v[70:73], off
	s_waitcnt lgkmcnt(0)

.LBB0_170:
	s_andn2_b64 vcc, exec, s[2:3]
	s_cbranch_vccnz .LBB0_172
	s_add_i32 s36, s31, s78
	s_cmp_gt_u32 s36, 0x2fff
	s_cbranch_scc1 .Lk_OUT_single
	s_add_i32 s0, s31, 0xfffff000
	s_lshr_b32 s0, s0, 1
	s_and_b32 s0, s0, 0x7fffffc0
	v_readlane_b32 s40, v254, 35
	s_and_b32 s4, s31, 0x7f
	s_lshl_b64 s[2:3], s[0:1], 14
	v_readlane_b32 s54, v254, 49
	v_readlane_b32 s55, v254, 50
	s_add_u32 s2, s54, s2
	s_addc_u32 s3, s55, s3
	s_lshl_b32 s5, s4, 7
	s_add_u32 s2, s2, s5
	s_addc_u32 s3, s3, 0
	v_lshl_add_u64 v[70:71], s[2:3], 0, v[142:143]
	v_lshlrev_b32_e32 v72, 2, v32
	v_mov_b32_e32 v73, v143
	v_lshl_add_u64 v[98:99], v[70:71], 0, v[72:73]
	v_add_co_u32_e32 v74, vcc, s22, v98
	v_add_u32_e32 v11, 0x420, v173
	s_nop 0
	v_addc_co_u32_e32 v75, vcc, 0, v99, vcc
	v_add_co_u32_e32 v78, vcc, s23, v98
	global_load_dwordx4 v[70:73], v[98:99], off
	s_nop 0
	global_load_dwordx4 v[74:77], v[74:75], off
	v_addc_co_u32_e32 v79, vcc, 0, v99, vcc
	v_add_co_u32_e32 v82, vcc, s24, v98
	v_add_u32_e32 v13, 0x428, v173
	s_nop 0
	v_addc_co_u32_e32 v83, vcc, 0, v99, vcc
	v_add_co_u32_e32 v86, vcc, s25, v98
	global_load_dwordx4 v[78:81], v[78:79], off
	s_nop 0
	global_load_dwordx4 v[82:85], v[82:83], off
	v_addc_co_u32_e32 v87, vcc, 0, v99, vcc
	v_add_co_u32_e32 v90, vcc, s26, v98
	v_add_u32_e32 v15, 0x840, v173
	s_nop 0
	v_addc_co_u32_e32 v91, vcc, 0, v99, vcc
	global_load_dwordx4 v[86:89], v[86:87], off
	s_nop 0
	global_load_dwordx4 v[90:93], v[90:91], off
	v_add_co_u32_e32 v94, vcc, s27, v98
	v_add_u32_e32 v33, 0x848, v173
	s_nop 0
	v_addc_co_u32_e32 v95, vcc, 0, v99, vcc
	global_load_dwordx4 v[94:97], v[94:95], off
	v_add_co_u32_e32 v98, vcc, s28, v98
	v_add_u32_e32 v47, 0xc60, v173
	s_nop 0
	v_addc_co_u32_e32 v99, vcc, 0, v99, vcc
	global_load_dwordx4 v[98:101], v[98:99], off
	s_add_i32 s31, s31, s78
	s_add_i32 s16, s16, s37
	s_add_i32 s17, s17, s18
	s_mov_b32 s69, 0
	s_add_i32 s68, s31, 0xfffff000
	s_lshr_b32 s68, s68, 1
	s_and_b32 s68, s68, 0x7fffffc0
	v_readlane_b32 s82, v254, 35
	s_and_b32 s72, s31, 0x7f
	s_lshl_b64 s[70:71], s[68:69], 14
	v_readlane_b32 s94, v254, 49
	v_readlane_b32 s95, v254, 50
	s_add_u32 s70, s94, s70
	s_addc_u32 s71, s95, s71
	s_lshl_b32 s73, s72, 7
	s_add_u32 s70, s70, s73
	s_addc_u32 s71, s71, 0
	v_lshl_add_u64 v[220:221], s[70:71], 0, v[142:143]
	v_lshlrev_b32_e32 v222, 2, v32
	v_mov_b32_e32 v223, v143
	v_lshl_add_u64 v[248:249], v[220:221], 0, v[222:223]
	v_add_co_u32_e32 v224, vcc, s22, v248
	v_add_u32_e32 v11, 0x420, v173
	s_nop 0
	v_addc_co_u32_e32 v225, vcc, 0, v249, vcc
	v_add_co_u32_e32 v228, vcc, s23, v248
	global_load_dwordx4 v[220:223], v[248:249], off
	s_nop 0
	global_load_dwordx4 v[224:227], v[224:225], off
	v_addc_co_u32_e32 v229, vcc, 0, v249, vcc
	v_add_co_u32_e32 v232, vcc, s24, v248
	v_add_u32_e32 v13, 0x428, v173
	s_nop 0
	v_addc_co_u32_e32 v233, vcc, 0, v249, vcc
	v_add_co_u32_e32 v236, vcc, s25, v248
	global_load_dwordx4 v[228:231], v[228:229], off
	s_nop 0
	global_load_dwordx4 v[232:235], v[232:233], off
	v_addc_co_u32_e32 v237, vcc, 0, v249, vcc
	v_add_co_u32_e32 v240, vcc, s26, v248
	v_add_u32_e32 v15, 0x840, v173
	s_nop 0
	v_addc_co_u32_e32 v241, vcc, 0, v249, vcc
	global_load_dwordx4 v[236:239], v[236:237], off
	s_nop 0
	global_load_dwordx4 v[240:243], v[240:241], off
	v_add_co_u32_e32 v244, vcc, s27, v248
	v_add_u32_e32 v33, 0x848, v173
	s_nop 0
	v_addc_co_u32_e32 v245, vcc, 0, v249, vcc
	global_load_dwordx4 v[244:247], v[244:245], off
	v_add_co_u32_e32 v248, vcc, s28, v248
	v_add_u32_e32 v47, 0xc60, v173
	s_nop 0
	v_addc_co_u32_e32 v249, vcc, 0, v249, vcc
	global_load_dwordx4 v[248:251], v[248:249], off
	s_sub_i32 s31, s31, s78
	s_sub_i32 s16, s16, s37
	s_sub_i32 s17, s17, s18
	v_add_u32_e32 v49, 0xc68, v173
	v_add_u32_e32 v51, 0x1080, v173
	v_add_u32_e32 v53, 0x1088, v173
	v_add_u32_e32 v55, 0x14a0, v173
	v_add_u32_e32 v57, 0x14a8, v173
	v_add_u32_e32 v59, 0x18c0, v173
	v_add_u32_e32 v61, 0x18c8, v173
	v_add_u32_e32 v63, 0x1ce0, v173
	v_add_u32_e32 v65, 0x1ce8, v173
	v_mov_b32_e32 v102, v143
	v_mov_b32_e32 v103, v143
	v_mov_b32_e32 v104, v143
	v_mov_b32_e32 v105, v143
	s_lshl_b32 s2, s4, 17
	s_add_u32 s2, s6, s2
	s_addc_u32 s3, s7, 0
	s_add_u32 s2, s2, s0
	s_addc_u32 s3, s3, 0
	v_readlane_b32 s41, v254, 36
	v_readlane_b32 s42, v254, 37
	v_readlane_b32 s43, v254, 38
	v_readlane_b32 s44, v254, 39
	v_readlane_b32 s45, v254, 40
	v_readlane_b32 s46, v254, 41
	v_readlane_b32 s47, v254, 42
	v_readlane_b32 s48, v254, 43
	v_readlane_b32 s49, v254, 44
	v_readlane_b32 s50, v254, 45
	v_readlane_b32 s51, v254, 46
	v_readlane_b32 s52, v254, 47
	v_readlane_b32 s53, v254, 48
	s_waitcnt vmcnt(15)
	ds_write2_b32 v173, v70, v71 offset1:1
	ds_write2_b32 v173, v72, v73 offset0:2 offset1:3
	s_waitcnt vmcnt(14)
	ds_write2_b32 v11, v74, v75 offset1:1
	ds_write2_b32 v13, v76, v77 offset1:1
	s_waitcnt vmcnt(13)
	ds_write2_b32 v15, v78, v79 offset1:1
	ds_write2_b32 v33, v80, v81 offset1:1
	s_waitcnt vmcnt(12)
	ds_write2_b32 v47, v82, v83 offset1:1
	ds_write2_b32 v49, v84, v85 offset1:1
	s_waitcnt vmcnt(11)
	ds_write2_b32 v51, v86, v87 offset1:1
	ds_write2_b32 v53, v88, v89 offset1:1
	s_waitcnt vmcnt(10)
	ds_write2_b32 v55, v90, v91 offset1:1
	ds_write2_b32 v57, v92, v93 offset1:1
	s_waitcnt vmcnt(9)
	ds_write2_b32 v59, v94, v95 offset1:1
	ds_write2_b32 v61, v96, v97 offset1:1
	s_waitcnt vmcnt(8)
	ds_write2_b32 v63, v98, v99 offset1:1
	ds_write2_b32 v65, v100, v101 offset1:1
	s_waitcnt lgkmcnt(0)
	ds_read2_b32 v[70:71], v149 offset1:16
	ds_read2_b32 v[72:73], v149 offset0:33 offset1:49
	ds_read2_b32 v[74:75], v149 offset0:66 offset1:82
	ds_read2_b32 v[76:77], v149 offset0:99 offset1:115
	ds_read2_b32 v[80:81], v149 offset0:132 offset1:148
	ds_read2_b32 v[82:83], v149 offset0:165 offset1:181
	ds_read2_b32 v[84:85], v149 offset0:198 offset1:214
	ds_read2_b32 v[86:87], v149 offset0:231 offset1:247
	s_waitcnt lgkmcnt(7)
	v_mul_f32_e32 v11, 0x44000000, v70
	s_waitcnt lgkmcnt(6)
	v_mul_f32_e32 v13, 0x44000000, v72
	v_med3_f32 v11, v11, s29, v9
	v_med3_f32 v13, v13, s29, v9
	v_cvt_pk_fp8_f32 v102, v11, v13
	s_waitcnt lgkmcnt(3)
	v_mul_f32_e32 v11, 0x44000000, v80
	s_waitcnt lgkmcnt(2)
	v_mul_f32_e32 v13, 0x44000000, v82
	v_med3_f32 v11, v11, s29, v9
	v_med3_f32 v13, v13, s29, v9
	v_mul_f32_e32 v15, 0x44000000, v74
	v_mul_f32_e32 v33, 0x44000000, v76
	v_cvt_pk_fp8_f32 v103, v11, v13
	v_add_u32_e32 v11, 0x400, v149
	v_med3_f32 v15, v15, s29, v9
	v_med3_f32 v33, v33, s29, v9
	ds_read2_b32 v[88:89], v11 offset0:8 offset1:24
	ds_read2_b32 v[90:91], v11 offset0:41 offset1:57
	ds_read2_b32 v[92:93], v11 offset0:74 offset1:90
	ds_read2_b32 v[94:95], v11 offset0:107 offset1:123
	v_cvt_pk_fp8_f32 v102, v15, v33 op_sel:[0,0,1]
	s_waitcnt lgkmcnt(5)
	v_mul_f32_e32 v15, 0x44000000, v84
	s_waitcnt lgkmcnt(4)
	v_mul_f32_e32 v33, 0x44000000, v86
	v_med3_f32 v15, v15, s29, v9
	v_med3_f32 v33, v33, s29, v9
	v_cvt_pk_fp8_f32 v103, v15, v33 op_sel:[0,0,1]
	s_waitcnt lgkmcnt(3)
	v_mul_f32_e32 v13, 0x44000000, v88
	s_waitcnt lgkmcnt(2)
	v_mul_f32_e32 v15, 0x44000000, v90
	v_med3_f32 v13, v13, s29, v9
	v_med3_f32 v15, v15, s29, v9
	v_cvt_pk_fp8_f32 v104, v13, v15
	ds_read2_b32 v[96:97], v11 offset0:140 offset1:156
	ds_read2_b32 v[98:99], v11 offset0:173 offset1:189
	ds_read2_b32 v[100:101], v11 offset0:206 offset1:222
	s_waitcnt lgkmcnt(4)
	v_mul_f32_e32 v33, 0x44000000, v92
	s_waitcnt lgkmcnt(3)
	v_mul_f32_e32 v47, 0x44000000, v94
	v_med3_f32 v33, v33, s29, v9
	v_med3_f32 v13, v47, s29, v9
	ds_read2_b32 v[106:107], v11 offset0:239 offset1:255
	v_cvt_pk_fp8_f32 v104, v33, v13 op_sel:[0,0,1]
	s_waitcnt lgkmcnt(3)
	v_mul_f32_e32 v13, 0x44000000, v96
	s_waitcnt lgkmcnt(2)
	v_mul_f32_e32 v15, 0x44000000, v98
	v_med3_f32 v11, v13, s29, v9
	v_med3_f32 v13, v15, s29, v9
	v_cvt_pk_fp8_f32 v105, v11, v13
	s_waitcnt lgkmcnt(1)
	v_mul_f32_e32 v33, 0x44000000, v100
	s_waitcnt lgkmcnt(0)
	v_mul_f32_e32 v11, 0x44000000, v106
	v_med3_f32 v13, v33, s29, v9
	v_med3_f32 v11, v11, s29, v9
	v_cvt_pk_fp8_f32 v105, v13, v11 op_sel:[0,0,1]
	v_mul_f32_e32 v11, 0x44000000, v71
	v_mul_f32_e32 v13, 0x44000000, v73
	v_med3_f32 v11, v11, s29, v9
	v_med3_f32 v13, v13, s29, v9
	v_mov_b32_e32 v70, v143
	v_cvt_pk_fp8_f32 v70, v11, v13
	v_mul_f32_e32 v15, 0x44000000, v75
	v_mul_f32_e32 v11, 0x44000000, v77
	v_med3_f32 v13, v15, s29, v9
	v_med3_f32 v11, v11, s29, v9
	v_cvt_pk_fp8_f32 v70, v13, v11 op_sel:[0,0,1]
	v_mul_f32_e32 v11, 0x44000000, v81
	v_mul_f32_e32 v13, 0x44000000, v83
	v_med3_f32 v11, v11, s29, v9
	v_med3_f32 v13, v13, s29, v9
	v_mov_b32_e32 v71, v143
	v_cvt_pk_fp8_f32 v71, v11, v13
	v_mul_f32_e32 v15, 0x44000000, v85
	v_mul_f32_e32 v11, 0x44000000, v87
	v_med3_f32 v13, v15, s29, v9
	v_med3_f32 v11, v11, s29, v9
	v_cvt_pk_fp8_f32 v71, v13, v11 op_sel:[0,0,1]
	v_mul_f32_e32 v11, 0x44000000, v89
	v_mul_f32_e32 v13, 0x44000000, v91
	v_med3_f32 v11, v11, s29, v9
	v_med3_f32 v13, v13, s29, v9
	v_mov_b32_e32 v72, v143
	v_cvt_pk_fp8_f32 v72, v11, v13
	v_mul_f32_e32 v15, 0x44000000, v93
	v_mul_f32_e32 v11, 0x44000000, v95
	v_med3_f32 v13, v15, s29, v9
	v_med3_f32 v11, v11, s29, v9
	v_cvt_pk_fp8_f32 v72, v13, v11 op_sel:[0,0,1]
	v_mul_f32_e32 v11, 0x44000000, v97
	v_mul_f32_e32 v13, 0x44000000, v99
	v_med3_f32 v11, v11, s29, v9
	v_med3_f32 v13, v13, s29, v9
	v_mov_b32_e32 v73, v143
	v_cvt_pk_fp8_f32 v73, v11, v13
	v_mul_f32_e32 v15, 0x44000000, v101
	v_mul_f32_e32 v11, 0x44000000, v107
	v_med3_f32 v13, v15, s29, v9
	v_med3_f32 v11, v11, s29, v9
	v_cvt_pk_fp8_f32 v73, v13, v11 op_sel:[0,0,1]
	v_lshl_add_u64 v[78:79], s[2:3], 0, v[144:145]
	v_lshl_add_u64 v[74:75], v[78:79], 0, v[36:37]
	global_store_dwordx4 v[74:75], v[102:105], off
	v_lshl_add_u64 v[74:75], v[78:79], 0, v[146:147]
	global_store_dwordx4 v[74:75], v[70:73], off
	s_waitcnt lgkmcnt(0)
	s_add_i32 s31, s31, s78
	s_add_i32 s16, s16, s37
	s_add_i32 s17, s17, s18
	s_add_i32 s0, s31, 0xfffff000
	s_lshr_b32 s0, s0, 1
	s_and_b32 s0, s0, 0x7fffffc0
	v_readlane_b32 s40, v254, 35
	s_and_b32 s4, s31, 0x7f
	s_lshl_b64 s[2:3], s[0:1], 14
	v_readlane_b32 s54, v254, 49
	v_readlane_b32 s55, v254, 50
	s_add_u32 s2, s54, s2
	s_addc_u32 s3, s55, s3
	s_lshl_b32 s5, s4, 7
	s_add_u32 s2, s2, s5
	s_addc_u32 s3, s3, 0
	v_lshl_add_u64 v[70:71], s[2:3], 0, v[142:143]
	v_lshlrev_b32_e32 v72, 2, v32
	v_mov_b32_e32 v73, v143
	v_lshl_add_u64 v[98:99], v[70:71], 0, v[72:73]
	v_add_co_u32_e32 v74, vcc, s22, v98
	v_add_u32_e32 v11, 0x420, v173
	s_nop 0
	v_addc_co_u32_e32 v75, vcc, 0, v99, vcc
	v_add_co_u32_e32 v78, vcc, s23, v98
	s_nop 0
	v_addc_co_u32_e32 v79, vcc, 0, v99, vcc
	v_add_co_u32_e32 v82, vcc, s24, v98
	v_add_u32_e32 v13, 0x428, v173
	s_nop 0
	v_addc_co_u32_e32 v83, vcc, 0, v99, vcc
	v_add_co_u32_e32 v86, vcc, s25, v98
	s_nop 0
	v_addc_co_u32_e32 v87, vcc, 0, v99, vcc
	v_add_co_u32_e32 v90, vcc, s26, v98
	v_add_u32_e32 v15, 0x840, v173
	s_nop 0
	v_addc_co_u32_e32 v91, vcc, 0, v99, vcc
	s_nop 0
	v_add_co_u32_e32 v94, vcc, s27, v98
	v_add_u32_e32 v33, 0x848, v173
	s_nop 0
	v_addc_co_u32_e32 v95, vcc, 0, v99, vcc
	v_add_co_u32_e32 v98, vcc, s28, v98
	v_add_u32_e32 v47, 0xc60, v173
	s_nop 0
	v_addc_co_u32_e32 v99, vcc, 0, v99, vcc
	v_add_u32_e32 v49, 0xc68, v173
	v_add_u32_e32 v51, 0x1080, v173
	v_add_u32_e32 v53, 0x1088, v173
	v_add_u32_e32 v55, 0x14a0, v173
	v_add_u32_e32 v57, 0x14a8, v173
	v_add_u32_e32 v59, 0x18c0, v173
	v_add_u32_e32 v61, 0x18c8, v173
	v_add_u32_e32 v63, 0x1ce0, v173
	v_add_u32_e32 v65, 0x1ce8, v173
	v_mov_b32_e32 v102, v143
	v_mov_b32_e32 v103, v143
	v_mov_b32_e32 v104, v143
	v_mov_b32_e32 v105, v143
	s_lshl_b32 s2, s4, 17
	s_add_u32 s2, s6, s2
	s_addc_u32 s3, s7, 0
	s_add_u32 s2, s2, s0
	s_addc_u32 s3, s3, 0
	v_readlane_b32 s41, v254, 36
	v_readlane_b32 s42, v254, 37
	v_readlane_b32 s43, v254, 38
	v_readlane_b32 s44, v254, 39
	v_readlane_b32 s45, v254, 40
	v_readlane_b32 s46, v254, 41
	v_readlane_b32 s47, v254, 42
	v_readlane_b32 s48, v254, 43
	v_readlane_b32 s49, v254, 44
	v_readlane_b32 s50, v254, 45
	v_readlane_b32 s51, v254, 46
	v_readlane_b32 s52, v254, 47
	v_readlane_b32 s53, v254, 48
	s_waitcnt vmcnt(9)
	ds_write2_b32 v173, v220, v221 offset1:1
	ds_write2_b32 v173, v222, v223 offset0:2 offset1:3
	s_waitcnt vmcnt(8)
	ds_write2_b32 v11, v224, v225 offset1:1
	ds_write2_b32 v13, v226, v227 offset1:1
	s_waitcnt vmcnt(7)
	ds_write2_b32 v15, v228, v229 offset1:1
	ds_write2_b32 v33, v230, v231 offset1:1
	s_waitcnt vmcnt(6)
	ds_write2_b32 v47, v232, v233 offset1:1
	ds_write2_b32 v49, v234, v235 offset1:1
	s_waitcnt vmcnt(5)
	ds_write2_b32 v51, v236, v237 offset1:1
	ds_write2_b32 v53, v238, v239 offset1:1
	s_waitcnt vmcnt(4)
	ds_write2_b32 v55, v240, v241 offset1:1
	ds_write2_b32 v57, v242, v243 offset1:1
	s_waitcnt vmcnt(3)
	ds_write2_b32 v59, v244, v245 offset1:1
	ds_write2_b32 v61, v246, v247 offset1:1
	s_waitcnt vmcnt(2)
	ds_write2_b32 v63, v248, v249 offset1:1
	ds_write2_b32 v65, v250, v251 offset1:1
	s_waitcnt lgkmcnt(0)
	ds_read2_b32 v[70:71], v149 offset1:16
	ds_read2_b32 v[72:73], v149 offset0:33 offset1:49
	ds_read2_b32 v[74:75], v149 offset0:66 offset1:82
	ds_read2_b32 v[76:77], v149 offset0:99 offset1:115
	ds_read2_b32 v[80:81], v149 offset0:132 offset1:148
	ds_read2_b32 v[82:83], v149 offset0:165 offset1:181
	ds_read2_b32 v[84:85], v149 offset0:198 offset1:214
	ds_read2_b32 v[86:87], v149 offset0:231 offset1:247
	s_waitcnt lgkmcnt(7)
	v_mul_f32_e32 v11, 0x44000000, v70
	s_waitcnt lgkmcnt(6)
	v_mul_f32_e32 v13, 0x44000000, v72
	v_med3_f32 v11, v11, s29, v9
	v_med3_f32 v13, v13, s29, v9
	v_cvt_pk_fp8_f32 v102, v11, v13
	s_waitcnt lgkmcnt(3)
	v_mul_f32_e32 v11, 0x44000000, v80
	s_waitcnt lgkmcnt(2)
	v_mul_f32_e32 v13, 0x44000000, v82
	v_med3_f32 v11, v11, s29, v9
	v_med3_f32 v13, v13, s29, v9
	v_mul_f32_e32 v15, 0x44000000, v74
	v_mul_f32_e32 v33, 0x44000000, v76
	v_cvt_pk_fp8_f32 v103, v11, v13
	v_add_u32_e32 v11, 0x400, v149
	v_med3_f32 v15, v15, s29, v9
	v_med3_f32 v33, v33, s29, v9
	ds_read2_b32 v[88:89], v11 offset0:8 offset1:24
	ds_read2_b32 v[90:91], v11 offset0:41 offset1:57
	ds_read2_b32 v[92:93], v11 offset0:74 offset1:90
	ds_read2_b32 v[94:95], v11 offset0:107 offset1:123
	v_cvt_pk_fp8_f32 v102, v15, v33 op_sel:[0,0,1]
	s_waitcnt lgkmcnt(5)
	v_mul_f32_e32 v15, 0x44000000, v84
	s_waitcnt lgkmcnt(4)
	v_mul_f32_e32 v33, 0x44000000, v86
	v_med3_f32 v15, v15, s29, v9
	v_med3_f32 v33, v33, s29, v9
	v_cvt_pk_fp8_f32 v103, v15, v33 op_sel:[0,0,1]
	s_waitcnt lgkmcnt(3)
	v_mul_f32_e32 v13, 0x44000000, v88
	s_waitcnt lgkmcnt(2)
	v_mul_f32_e32 v15, 0x44000000, v90
	v_med3_f32 v13, v13, s29, v9
	v_med3_f32 v15, v15, s29, v9
	v_cvt_pk_fp8_f32 v104, v13, v15
	ds_read2_b32 v[96:97], v11 offset0:140 offset1:156
	ds_read2_b32 v[98:99], v11 offset0:173 offset1:189
	ds_read2_b32 v[100:101], v11 offset0:206 offset1:222
	s_waitcnt lgkmcnt(4)
	v_mul_f32_e32 v33, 0x44000000, v92
	s_waitcnt lgkmcnt(3)
	v_mul_f32_e32 v47, 0x44000000, v94
	v_med3_f32 v33, v33, s29, v9
	v_med3_f32 v13, v47, s29, v9
	ds_read2_b32 v[106:107], v11 offset0:239 offset1:255
	v_cvt_pk_fp8_f32 v104, v33, v13 op_sel:[0,0,1]
	s_waitcnt lgkmcnt(3)
	v_mul_f32_e32 v13, 0x44000000, v96
	s_waitcnt lgkmcnt(2)
	v_mul_f32_e32 v15, 0x44000000, v98
	v_med3_f32 v11, v13, s29, v9
	v_med3_f32 v13, v15, s29, v9
	v_cvt_pk_fp8_f32 v105, v11, v13
	s_waitcnt lgkmcnt(1)
	v_mul_f32_e32 v33, 0x44000000, v100
	s_waitcnt lgkmcnt(0)
	v_mul_f32_e32 v11, 0x44000000, v106
	v_med3_f32 v13, v33, s29, v9
	v_med3_f32 v11, v11, s29, v9
	v_cvt_pk_fp8_f32 v105, v13, v11 op_sel:[0,0,1]
	v_mul_f32_e32 v11, 0x44000000, v71
	v_mul_f32_e32 v13, 0x44000000, v73
	v_med3_f32 v11, v11, s29, v9
	v_med3_f32 v13, v13, s29, v9
	v_mov_b32_e32 v70, v143
	v_cvt_pk_fp8_f32 v70, v11, v13
	v_mul_f32_e32 v15, 0x44000000, v75
	v_mul_f32_e32 v11, 0x44000000, v77
	v_med3_f32 v13, v15, s29, v9
	v_med3_f32 v11, v11, s29, v9
	v_cvt_pk_fp8_f32 v70, v13, v11 op_sel:[0,0,1]
	v_mul_f32_e32 v11, 0x44000000, v81
	v_mul_f32_e32 v13, 0x44000000, v83
	v_med3_f32 v11, v11, s29, v9
	v_med3_f32 v13, v13, s29, v9
	v_mov_b32_e32 v71, v143
	v_cvt_pk_fp8_f32 v71, v11, v13
	v_mul_f32_e32 v15, 0x44000000, v85
	v_mul_f32_e32 v11, 0x44000000, v87
	v_med3_f32 v13, v15, s29, v9
	v_med3_f32 v11, v11, s29, v9
	v_cvt_pk_fp8_f32 v71, v13, v11 op_sel:[0,0,1]
	v_mul_f32_e32 v11, 0x44000000, v89
	v_mul_f32_e32 v13, 0x44000000, v91
	v_med3_f32 v11, v11, s29, v9
	v_med3_f32 v13, v13, s29, v9
	v_mov_b32_e32 v72, v143
	v_cvt_pk_fp8_f32 v72, v11, v13
	v_mul_f32_e32 v15, 0x44000000, v93
	v_mul_f32_e32 v11, 0x44000000, v95
	v_med3_f32 v13, v15, s29, v9
	v_med3_f32 v11, v11, s29, v9
	v_cvt_pk_fp8_f32 v72, v13, v11 op_sel:[0,0,1]
	v_mul_f32_e32 v11, 0x44000000, v97
	v_mul_f32_e32 v13, 0x44000000, v99
	v_med3_f32 v11, v11, s29, v9
	v_med3_f32 v13, v13, s29, v9
	v_mov_b32_e32 v73, v143
	v_cvt_pk_fp8_f32 v73, v11, v13
	v_mul_f32_e32 v15, 0x44000000, v101
	v_mul_f32_e32 v11, 0x44000000, v107
	v_med3_f32 v13, v15, s29, v9
	v_med3_f32 v11, v11, s29, v9
	v_cvt_pk_fp8_f32 v73, v13, v11 op_sel:[0,0,1]
	v_lshl_add_u64 v[78:79], s[2:3], 0, v[144:145]
	v_lshl_add_u64 v[74:75], v[78:79], 0, v[36:37]
	global_store_dwordx4 v[74:75], v[102:105], off
	v_lshl_add_u64 v[74:75], v[78:79], 0, v[146:147]
	global_store_dwordx4 v[74:75], v[70:73], off
	s_waitcnt lgkmcnt(0)
	s_branch .LBB0_172
.Lk_OUT_single:
	s_add_i32 s0, s31, 0xfffff000
	s_lshr_b32 s0, s0, 1
	s_and_b32 s0, s0, 0x7fffffc0
	v_readlane_b32 s40, v254, 35
	s_and_b32 s4, s31, 0x7f
	s_lshl_b64 s[2:3], s[0:1], 14
	v_readlane_b32 s54, v254, 49
	v_readlane_b32 s55, v254, 50
	s_add_u32 s2, s54, s2
	s_addc_u32 s3, s55, s3
	s_lshl_b32 s5, s4, 7
	s_add_u32 s2, s2, s5
	s_addc_u32 s3, s3, 0
	v_lshl_add_u64 v[70:71], s[2:3], 0, v[142:143]
	v_lshlrev_b32_e32 v72, 2, v32
	v_mov_b32_e32 v73, v143
	v_lshl_add_u64 v[98:99], v[70:71], 0, v[72:73]
	v_add_co_u32_e32 v74, vcc, s22, v98
	v_add_u32_e32 v11, 0x420, v173
	s_nop 0
	v_addc_co_u32_e32 v75, vcc, 0, v99, vcc
	v_add_co_u32_e32 v78, vcc, s23, v98
	global_load_dwordx4 v[70:73], v[98:99], off
	s_nop 0
	global_load_dwordx4 v[74:77], v[74:75], off
	v_addc_co_u32_e32 v79, vcc, 0, v99, vcc
	v_add_co_u32_e32 v82, vcc, s24, v98
	v_add_u32_e32 v13, 0x428, v173
	s_nop 0
	v_addc_co_u32_e32 v83, vcc, 0, v99, vcc
	v_add_co_u32_e32 v86, vcc, s25, v98
	global_load_dwordx4 v[78:81], v[78:79], off
	s_nop 0
	global_load_dwordx4 v[82:85], v[82:83], off
	v_addc_co_u32_e32 v87, vcc, 0, v99, vcc
	v_add_co_u32_e32 v90, vcc, s26, v98
	v_add_u32_e32 v15, 0x840, v173
	s_nop 0
	v_addc_co_u32_e32 v91, vcc, 0, v99, vcc
	global_load_dwordx4 v[86:89], v[86:87], off
	s_nop 0
	global_load_dwordx4 v[90:93], v[90:91], off
	v_add_co_u32_e32 v94, vcc, s27, v98
	v_add_u32_e32 v33, 0x848, v173
	s_nop 0
	v_addc_co_u32_e32 v95, vcc, 0, v99, vcc
	global_load_dwordx4 v[94:97], v[94:95], off
	v_add_co_u32_e32 v98, vcc, s28, v98
	v_add_u32_e32 v47, 0xc60, v173
	s_nop 0
	v_addc_co_u32_e32 v99, vcc, 0, v99, vcc
	global_load_dwordx4 v[98:101], v[98:99], off
	v_add_u32_e32 v49, 0xc68, v173
	v_add_u32_e32 v51, 0x1080, v173
	v_add_u32_e32 v53, 0x1088, v173
	v_add_u32_e32 v55, 0x14a0, v173
	v_add_u32_e32 v57, 0x14a8, v173
	v_add_u32_e32 v59, 0x18c0, v173
	v_add_u32_e32 v61, 0x18c8, v173
	v_add_u32_e32 v63, 0x1ce0, v173
	v_add_u32_e32 v65, 0x1ce8, v173
	v_mov_b32_e32 v102, v143
	v_mov_b32_e32 v103, v143
	v_mov_b32_e32 v104, v143
	v_mov_b32_e32 v105, v143
	s_lshl_b32 s2, s4, 17
	s_add_u32 s2, s6, s2
	s_addc_u32 s3, s7, 0
	s_add_u32 s2, s2, s0
	s_addc_u32 s3, s3, 0
	v_readlane_b32 s41, v254, 36
	v_readlane_b32 s42, v254, 37
	v_readlane_b32 s43, v254, 38
	v_readlane_b32 s44, v254, 39
	v_readlane_b32 s45, v254, 40
	v_readlane_b32 s46, v254, 41
	v_readlane_b32 s47, v254, 42
	v_readlane_b32 s48, v254, 43
	v_readlane_b32 s49, v254, 44
	v_readlane_b32 s50, v254, 45
	v_readlane_b32 s51, v254, 46
	v_readlane_b32 s52, v254, 47
	v_readlane_b32 s53, v254, 48
	s_waitcnt vmcnt(7)
	ds_write2_b32 v173, v70, v71 offset1:1
	ds_write2_b32 v173, v72, v73 offset0:2 offset1:3
	s_waitcnt vmcnt(6)
	ds_write2_b32 v11, v74, v75 offset1:1
	ds_write2_b32 v13, v76, v77 offset1:1
	s_waitcnt vmcnt(5)
	ds_write2_b32 v15, v78, v79 offset1:1
	ds_write2_b32 v33, v80, v81 offset1:1
	s_waitcnt vmcnt(4)
	ds_write2_b32 v47, v82, v83 offset1:1
	ds_write2_b32 v49, v84, v85 offset1:1
	s_waitcnt vmcnt(3)
	ds_write2_b32 v51, v86, v87 offset1:1
	ds_write2_b32 v53, v88, v89 offset1:1
	s_waitcnt vmcnt(2)
	ds_write2_b32 v55, v90, v91 offset1:1
	ds_write2_b32 v57, v92, v93 offset1:1
	s_waitcnt vmcnt(1)
	ds_write2_b32 v59, v94, v95 offset1:1
	ds_write2_b32 v61, v96, v97 offset1:1
	s_waitcnt vmcnt(0)
	ds_write2_b32 v63, v98, v99 offset1:1
	ds_write2_b32 v65, v100, v101 offset1:1
	s_waitcnt lgkmcnt(0)
	ds_read2_b32 v[70:71], v149 offset1:16
	ds_read2_b32 v[72:73], v149 offset0:33 offset1:49
	ds_read2_b32 v[74:75], v149 offset0:66 offset1:82
	ds_read2_b32 v[76:77], v149 offset0:99 offset1:115
	ds_read2_b32 v[80:81], v149 offset0:132 offset1:148
	ds_read2_b32 v[82:83], v149 offset0:165 offset1:181
	ds_read2_b32 v[84:85], v149 offset0:198 offset1:214
	ds_read2_b32 v[86:87], v149 offset0:231 offset1:247
	s_waitcnt lgkmcnt(7)
	v_mul_f32_e32 v11, 0x44000000, v70
	s_waitcnt lgkmcnt(6)
	v_mul_f32_e32 v13, 0x44000000, v72
	v_med3_f32 v11, v11, s29, v9
	v_med3_f32 v13, v13, s29, v9
	v_cvt_pk_fp8_f32 v102, v11, v13
	s_waitcnt lgkmcnt(3)
	v_mul_f32_e32 v11, 0x44000000, v80
	s_waitcnt lgkmcnt(2)
	v_mul_f32_e32 v13, 0x44000000, v82
	v_med3_f32 v11, v11, s29, v9
	v_med3_f32 v13, v13, s29, v9
	v_mul_f32_e32 v15, 0x44000000, v74
	v_mul_f32_e32 v33, 0x44000000, v76
	v_cvt_pk_fp8_f32 v103, v11, v13
	v_add_u32_e32 v11, 0x400, v149
	v_med3_f32 v15, v15, s29, v9
	v_med3_f32 v33, v33, s29, v9
	ds_read2_b32 v[88:89], v11 offset0:8 offset1:24
	ds_read2_b32 v[90:91], v11 offset0:41 offset1:57
	ds_read2_b32 v[92:93], v11 offset0:74 offset1:90
	ds_read2_b32 v[94:95], v11 offset0:107 offset1:123
	v_cvt_pk_fp8_f32 v102, v15, v33 op_sel:[0,0,1]
	s_waitcnt lgkmcnt(5)
	v_mul_f32_e32 v15, 0x44000000, v84
	s_waitcnt lgkmcnt(4)
	v_mul_f32_e32 v33, 0x44000000, v86
	v_med3_f32 v15, v15, s29, v9
	v_med3_f32 v33, v33, s29, v9
	v_cvt_pk_fp8_f32 v103, v15, v33 op_sel:[0,0,1]
	s_waitcnt lgkmcnt(3)
	v_mul_f32_e32 v13, 0x44000000, v88
	s_waitcnt lgkmcnt(2)
	v_mul_f32_e32 v15, 0x44000000, v90
	v_med3_f32 v13, v13, s29, v9
	v_med3_f32 v15, v15, s29, v9
	v_cvt_pk_fp8_f32 v104, v13, v15
	ds_read2_b32 v[96:97], v11 offset0:140 offset1:156
	ds_read2_b32 v[98:99], v11 offset0:173 offset1:189
	ds_read2_b32 v[100:101], v11 offset0:206 offset1:222
	s_waitcnt lgkmcnt(4)
	v_mul_f32_e32 v33, 0x44000000, v92
	s_waitcnt lgkmcnt(3)
	v_mul_f32_e32 v47, 0x44000000, v94
	v_med3_f32 v33, v33, s29, v9
	v_med3_f32 v13, v47, s29, v9
	ds_read2_b32 v[106:107], v11 offset0:239 offset1:255
	v_cvt_pk_fp8_f32 v104, v33, v13 op_sel:[0,0,1]
	s_waitcnt lgkmcnt(3)
	v_mul_f32_e32 v13, 0x44000000, v96
	s_waitcnt lgkmcnt(2)
	v_mul_f32_e32 v15, 0x44000000, v98
	v_med3_f32 v11, v13, s29, v9
	v_med3_f32 v13, v15, s29, v9
	v_cvt_pk_fp8_f32 v105, v11, v13
	s_waitcnt lgkmcnt(1)
	v_mul_f32_e32 v33, 0x44000000, v100
	s_waitcnt lgkmcnt(0)
	v_mul_f32_e32 v11, 0x44000000, v106
	v_med3_f32 v13, v33, s29, v9
	v_med3_f32 v11, v11, s29, v9
	v_cvt_pk_fp8_f32 v105, v13, v11 op_sel:[0,0,1]
	v_mul_f32_e32 v11, 0x44000000, v71
	v_mul_f32_e32 v13, 0x44000000, v73
	v_med3_f32 v11, v11, s29, v9
	v_med3_f32 v13, v13, s29, v9
	v_mov_b32_e32 v70, v143
	v_cvt_pk_fp8_f32 v70, v11, v13
	v_mul_f32_e32 v15, 0x44000000, v75
	v_mul_f32_e32 v11, 0x44000000, v77
	v_med3_f32 v13, v15, s29, v9
	v_med3_f32 v11, v11, s29, v9
	v_cvt_pk_fp8_f32 v70, v13, v11 op_sel:[0,0,1]
	v_mul_f32_e32 v11, 0x44000000, v81
	v_mul_f32_e32 v13, 0x44000000, v83
	v_med3_f32 v11, v11, s29, v9
	v_med3_f32 v13, v13, s29, v9
	v_mov_b32_e32 v71, v143
	v_cvt_pk_fp8_f32 v71, v11, v13
	v_mul_f32_e32 v15, 0x44000000, v85
	v_mul_f32_e32 v11, 0x44000000, v87
	v_med3_f32 v13, v15, s29, v9
	v_med3_f32 v11, v11, s29, v9
	v_cvt_pk_fp8_f32 v71, v13, v11 op_sel:[0,0,1]
	v_mul_f32_e32 v11, 0x44000000, v89
	v_mul_f32_e32 v13, 0x44000000, v91
	v_med3_f32 v11, v11, s29, v9
	v_med3_f32 v13, v13, s29, v9
	v_mov_b32_e32 v72, v143
	v_cvt_pk_fp8_f32 v72, v11, v13
	v_mul_f32_e32 v15, 0x44000000, v93
	v_mul_f32_e32 v11, 0x44000000, v95
	v_med3_f32 v13, v15, s29, v9
	v_med3_f32 v11, v11, s29, v9
	v_cvt_pk_fp8_f32 v72, v13, v11 op_sel:[0,0,1]
	v_mul_f32_e32 v11, 0x44000000, v97
	v_mul_f32_e32 v13, 0x44000000, v99
	v_med3_f32 v11, v11, s29, v9
	v_med3_f32 v13, v13, s29, v9
	v_mov_b32_e32 v73, v143
	v_cvt_pk_fp8_f32 v73, v11, v13
	v_mul_f32_e32 v15, 0x44000000, v101
	v_mul_f32_e32 v11, 0x44000000, v107
	v_med3_f32 v13, v15, s29, v9
	v_med3_f32 v11, v11, s29, v9
	v_cvt_pk_fp8_f32 v73, v13, v11 op_sel:[0,0,1]
	v_lshl_add_u64 v[78:79], s[2:3], 0, v[144:145]
	v_lshl_add_u64 v[74:75], v[78:79], 0, v[36:37]
	global_store_dwordx4 v[74:75], v[102:105], off
	v_lshl_add_u64 v[74:75], v[78:79], 0, v[146:147]
	global_store_dwordx4 v[74:75], v[70:73], off
	s_waitcnt lgkmcnt(0)

.LBB0_175:
	s_cmp_eq_u32 s32, 0
	s_cbranch_scc1 .Lp0_done_mode0
	s_waitcnt vmcnt(0) lgkmcnt(0)
	s_barrier
	s_mov_b32 s32, 0
	s_add_i32 s2, s97, 0x70
	s_lshl_b32 s2, s2, 11
	v_lshl_add_u32 v209, v0, 2, s2
	s_add_u32 s2, s76, 0x30c00000
	s_addc_u32 s3, s77, 0
	global_load_dword v210, v209, s[2:3]
	s_add_u32 s2, s2, 0x80000
	s_addc_u32 s3, s3, 0
	global_load_dword v211, v209, s[2:3]
	s_add_u32 s2, s2, 0x80000
	s_addc_u32 s3, s3, 0
	global_load_dword v0, v209, s[2:3]
	s_add_u32 s2, s2, 0x80000
	s_addc_u32 s3, s3, 0
	global_load_dword v1, v209, s[2:3]
	s_add_u32 s2, s2, 0x80000
	s_addc_u32 s3, s3, 0
	global_load_dword v5, v209, s[2:3]
	s_add_u32 s2, s2, 0x80000
	s_addc_u32 s3, s3, 0
	global_load_dword v6, v209, s[2:3]
	s_add_u32 s2, s2, 0x80000
	s_addc_u32 s3, s3, 0
	global_load_dword v8, v209, s[2:3]
	s_add_u32 s2, s2, 0x80000
	s_addc_u32 s3, s3, 0
	global_load_dword v36, v209, s[2:3]
	s_add_u32 s2, s2, 0x80000
	s_addc_u32 s3, s3, 0
	global_load_dword v37, v209, s[2:3]
	s_add_u32 s2, s2, 0x80000
	s_addc_u32 s3, s3, 0
	global_load_dword v38, v209, s[2:3]
	s_add_u32 s2, s2, 0x80000
	s_addc_u32 s3, s3, 0
	global_load_dword v39, v209, s[2:3]
	s_add_u32 s2, s2, 0x80000
	s_addc_u32 s3, s3, 0
	global_load_dword v40, v209, s[2:3]
	s_add_u32 s2, s2, 0x80000
	s_addc_u32 s3, s3, 0
	global_load_dword v41, v209, s[2:3]
	s_add_u32 s2, s2, 0x80000
	s_addc_u32 s3, s3, 0
	global_load_dword v42, v209, s[2:3]
	s_add_u32 s2, s2, 0x80000
	s_addc_u32 s3, s3, 0
	global_load_dword v43, v209, s[2:3]
	s_add_u32 s2, s2, 0x80000
	s_addc_u32 s3, s3, 0
	global_load_dword v44, v209, s[2:3]
	s_add_u32 s2, s2, 0x80000
	s_addc_u32 s3, s3, 0
	global_load_dword v45, v209, s[2:3]
	s_add_u32 s2, s2, 0x80000
	s_addc_u32 s3, s3, 0
	global_load_dword v50, v209, s[2:3]
	s_add_u32 s2, s2, 0x80000
	s_addc_u32 s3, s3, 0
	global_load_dword v51, v209, s[2:3]
	s_add_u32 s2, s2, 0x80000
	s_addc_u32 s3, s3, 0
	global_load_dword v52, v209, s[2:3]
	s_add_u32 s2, s2, 0x80000
	s_addc_u32 s3, s3, 0
	global_load_dword v53, v209, s[2:3]
	s_add_u32 s2, s2, 0x80000
	s_addc_u32 s3, s3, 0
	global_load_dword v54, v209, s[2:3]
	s_add_u32 s2, s2, 0x80000
	s_addc_u32 s3, s3, 0
	global_load_dword v55, v209, s[2:3]
	s_add_u32 s2, s2, 0x80000
	s_addc_u32 s3, s3, 0
	global_load_dword v56, v209, s[2:3]
	s_add_u32 s2, s2, 0x80000
	s_addc_u32 s3, s3, 0
	global_load_dword v57, v209, s[2:3]
	s_add_u32 s2, s2, 0x80000
	s_addc_u32 s3, s3, 0
	global_load_dword v62, v209, s[2:3]
	s_add_u32 s2, s2, 0x80000
	s_addc_u32 s3, s3, 0
	global_load_dword v63, v209, s[2:3]
	s_add_u32 s2, s2, 0x80000
	s_addc_u32 s3, s3, 0
	global_load_dword v64, v209, s[2:3]
	s_add_u32 s2, s2, 0x80000
	s_addc_u32 s3, s3, 0
	global_load_dword v65, v209, s[2:3]
	s_add_u32 s2, s2, 0x80000
	s_addc_u32 s3, s3, 0
	global_load_dword v70, v209, s[2:3]
	s_add_u32 s2, s2, 0x80000
	s_addc_u32 s3, s3, 0
	global_load_dword v71, v209, s[2:3]
	s_add_u32 s2, s2, 0x80000
	s_addc_u32 s3, s3, 0
	global_load_dword v72, v209, s[2:3]
	s_add_u32 s2, s2, 0x80000
	s_addc_u32 s3, s3, 0
	global_load_dword v73, v209, s[2:3]
	s_add_u32 s2, s2, 0x80000
	s_addc_u32 s3, s3, 0
	global_load_dword v82, v209, s[2:3]
	s_add_u32 s2, s2, 0x80000
	s_addc_u32 s3, s3, 0
	global_load_dword v83, v209, s[2:3]
	s_add_u32 s2, s2, 0x80000
	s_addc_u32 s3, s3, 0
	global_load_dword v84, v209, s[2:3]
	s_add_u32 s2, s2, 0x80000
	s_addc_u32 s3, s3, 0
	global_load_dword v85, v209, s[2:3]
	s_add_u32 s2, s2, 0x80000
	s_addc_u32 s3, s3, 0
	global_load_dword v88, v209, s[2:3]
	s_add_u32 s2, s2, 0x80000
	s_addc_u32 s3, s3, 0
	global_load_dword v89, v209, s[2:3]
	s_add_u32 s2, s2, 0x80000
	s_addc_u32 s3, s3, 0
	global_load_dword v94, v209, s[2:3]
	s_add_u32 s2, s2, 0x80000
	s_addc_u32 s3, s3, 0
	global_load_dword v95, v209, s[2:3]
	s_add_u32 s2, s2, 0x80000
	s_addc_u32 s3, s3, 0
	global_load_dword v96, v209, s[2:3]
	s_add_u32 s2, s2, 0x80000
	s_addc_u32 s3, s3, 0
	global_load_dword v97, v209, s[2:3]
	s_add_u32 s2, s2, 0x80000
	s_addc_u32 s3, s3, 0
	global_load_dword v102, v209, s[2:3]
	s_add_u32 s2, s2, 0x80000
	s_addc_u32 s3, s3, 0
	global_load_dword v103, v209, s[2:3]
	s_add_u32 s2, s2, 0x80000
	s_addc_u32 s3, s3, 0
	global_load_dword v104, v209, s[2:3]
	s_add_u32 s2, s2, 0x80000
	s_addc_u32 s3, s3, 0
	global_load_dword v105, v209, s[2:3]
	s_add_u32 s2, s2, 0x80000
	s_addc_u32 s3, s3, 0
	global_load_dword v122, v209, s[2:3]
	s_add_u32 s2, s2, 0x80000
	s_addc_u32 s3, s3, 0
	global_load_dword v123, v209, s[2:3]
	s_add_u32 s2, s2, 0x80000
	s_addc_u32 s3, s3, 0
	global_load_dword v124, v209, s[2:3]
	s_add_u32 s2, s2, 0x80000
	s_addc_u32 s3, s3, 0
	global_load_dword v125, v209, s[2:3]
	s_add_u32 s2, s2, 0x80000
	s_addc_u32 s3, s3, 0
	global_load_dword v170, v209, s[2:3]
	s_add_u32 s2, s2, 0x80000
	s_addc_u32 s3, s3, 0
	global_load_dword v171, v209, s[2:3]
	s_add_u32 s2, s2, 0x80000
	s_addc_u32 s3, s3, 0
	global_load_dword v172, v209, s[2:3]
	s_add_u32 s2, s2, 0x80000
	s_addc_u32 s3, s3, 0
	global_load_dword v173, v209, s[2:3]
	s_add_u32 s2, s2, 0x80000
	s_addc_u32 s3, s3, 0
	global_load_dword v174, v209, s[2:3]
	s_add_u32 s2, s2, 0x80000
	s_addc_u32 s3, s3, 0
	global_load_dword v175, v209, s[2:3]
	s_add_u32 s2, s2, 0x80000
	s_addc_u32 s3, s3, 0
	global_load_dword v195, v209, s[2:3]
	s_add_u32 s2, s2, 0x80000
	s_addc_u32 s3, s3, 0
	global_load_dword v197, v209, s[2:3]
	s_add_u32 s2, s2, 0x80000
	s_addc_u32 s3, s3, 0
	global_load_dword v254, v209, s[2:3]
	s_add_u32 s2, s2, 0x80000
	s_addc_u32 s3, s3, 0
	global_load_dword v255, v209, s[2:3]
	s_waitcnt vmcnt(0)
	v_readlane_b32 s64, v211, 0
	v_readlane_b32 s65, v211, 1
	v_readlane_b32 s66, v211, 2
	v_readlane_b32 s67, v211, 3
	v_readlane_b32 s68, v211, 4
	v_readlane_b32 s69, v211, 5
	v_readlane_b32 s70, v211, 6
	v_readlane_b32 s71, v211, 7
	v_readlane_b32 s72, v211, 8
	v_readlane_b32 s73, v211, 9
	v_readlane_b32 s74, v211, 10
	v_readlane_b32 s75, v211, 11
	v_readlane_b32 s76, v211, 12
	v_readlane_b32 s77, v211, 13
	v_readlane_b32 s78, v211, 14
	v_readlane_b32 s79, v211, 15
	v_readlane_b32 s80, v211, 16
	v_readlane_b32 s81, v211, 17
	v_readlane_b32 s82, v211, 18
	v_readlane_b32 s83, v211, 19
	v_readlane_b32 s84, v211, 20
	v_readlane_b32 s85, v211, 21
	v_readlane_b32 s86, v211, 22
	v_readlane_b32 s87, v211, 23
	v_readlane_b32 s88, v211, 24
	v_readlane_b32 s89, v211, 25
	v_readlane_b32 s90, v211, 26
	v_readlane_b32 s91, v211, 27
	v_readlane_b32 s92, v211, 28
	v_readlane_b32 s93, v211, 29
	v_readlane_b32 s94, v211, 30
	v_readlane_b32 s95, v211, 31
	v_readlane_b32 s96, v211, 32
	v_readlane_b32 s97, v211, 33
	v_readlane_b32 s0, v210, 0
	v_readlane_b32 s1, v210, 1
	v_readlane_b32 s2, v210, 2
	v_readlane_b32 s3, v210, 3
	v_readlane_b32 s4, v210, 4
	v_readlane_b32 s5, v210, 5
	v_readlane_b32 s6, v210, 6
	v_readlane_b32 s7, v210, 7
	v_readlane_b32 s8, v210, 8
	v_readlane_b32 s9, v210, 9
	v_readlane_b32 s10, v210, 10
	v_readlane_b32 s11, v210, 11
	v_readlane_b32 s12, v210, 12
	v_readlane_b32 s13, v210, 13
	v_readlane_b32 s14, v210, 14
	v_readlane_b32 s15, v210, 15
	v_readlane_b32 s16, v210, 16
	v_readlane_b32 s17, v210, 17
	v_readlane_b32 s18, v210, 18
	v_readlane_b32 s19, v210, 19
	v_readlane_b32 s20, v210, 20
	v_readlane_b32 s21, v210, 21
	v_readlane_b32 s22, v210, 22
	v_readlane_b32 s23, v210, 23
	v_readlane_b32 s24, v210, 24
	v_readlane_b32 s25, v210, 25
	v_readlane_b32 s26, v210, 26
	v_readlane_b32 s27, v210, 27
	v_readlane_b32 s28, v210, 28
	v_readlane_b32 s29, v210, 29
	v_readlane_b32 s30, v210, 30
	v_readlane_b32 s31, v210, 31
	v_readlane_b32 s33, v210, 33
	v_readlane_b32 s34, v210, 34
	v_readlane_b32 s35, v210, 35
	v_readlane_b32 s36, v210, 36
	v_readlane_b32 s37, v210, 37
	v_readlane_b32 s38, v210, 38
	v_readlane_b32 s39, v210, 39
	v_readlane_b32 s40, v210, 40
	v_readlane_b32 s41, v210, 41
	v_readlane_b32 s42, v210, 42
	v_readlane_b32 s43, v210, 43
	v_readlane_b32 s44, v210, 44
	v_readlane_b32 s45, v210, 45
	v_readlane_b32 s46, v210, 46
	v_readlane_b32 s47, v210, 47
	v_readlane_b32 s48, v210, 48
	v_readlane_b32 s49, v210, 49
	v_readlane_b32 s50, v210, 50
	v_readlane_b32 s51, v210, 51
	v_readlane_b32 s52, v210, 52
	v_readlane_b32 s53, v210, 53
	v_readlane_b32 s54, v210, 54
	v_readlane_b32 s55, v210, 55
	v_readlane_b32 s56, v210, 56
	v_readlane_b32 s57, v210, 57
	v_readlane_b32 s58, v210, 58
	v_readlane_b32 s59, v210, 59
	v_readlane_b32 s60, v210, 60
	v_readlane_b32 s61, v210, 61
	v_readlane_b32 s62, v210, 62
	v_readlane_b32 s63, v210, 63
	s_nop 4
	s_branch .LBB0_361

.Lstream_call:
	v_writelane_b32 v2, s0, 0
	v_writelane_b32 v2, s1, 1
	v_writelane_b32 v2, s2, 2
	v_writelane_b32 v2, s3, 3
	v_writelane_b32 v2, s4, 4
	v_writelane_b32 v2, s5, 5
	v_writelane_b32 v2, s6, 6
	v_writelane_b32 v2, s7, 7
	v_writelane_b32 v2, s8, 8
	v_writelane_b32 v2, s9, 9
	v_writelane_b32 v2, s10, 10
	v_writelane_b32 v2, s11, 11
	v_writelane_b32 v2, s12, 12
	v_writelane_b32 v2, s13, 13
	v_writelane_b32 v2, s14, 14
	v_writelane_b32 v2, s15, 15
	v_writelane_b32 v2, s16, 16
	v_writelane_b32 v2, s17, 17
	v_writelane_b32 v2, s18, 18
	v_writelane_b32 v2, s19, 19
	v_writelane_b32 v2, s20, 20
	v_writelane_b32 v2, s21, 21
	v_writelane_b32 v2, s22, 22
	v_writelane_b32 v2, s23, 23
	v_writelane_b32 v2, s24, 24
	v_writelane_b32 v2, s25, 25
	v_writelane_b32 v2, s26, 26
	v_writelane_b32 v2, s27, 27
	v_writelane_b32 v2, s28, 28
	v_writelane_b32 v2, s29, 29
	v_writelane_b32 v2, s30, 30
	v_writelane_b32 v2, s31, 31
	v_writelane_b32 v2, s32, 32
	v_writelane_b32 v2, s33, 33
	v_writelane_b32 v2, s34, 34
	v_writelane_b32 v2, s35, 35
	v_writelane_b32 v2, s36, 36
	v_writelane_b32 v2, s37, 37
	v_writelane_b32 v2, s38, 38
	v_writelane_b32 v2, s39, 39
	v_writelane_b32 v2, s40, 40
	v_writelane_b32 v2, s41, 41
	v_writelane_b32 v2, s42, 42
	v_writelane_b32 v2, s43, 43
	v_writelane_b32 v2, s44, 44
	v_writelane_b32 v2, s45, 45
	v_writelane_b32 v2, s46, 46
	v_writelane_b32 v2, s47, 47
	v_writelane_b32 v2, s48, 48
	v_writelane_b32 v2, s49, 49
	v_writelane_b32 v2, s50, 50
	v_writelane_b32 v2, s51, 51
	v_writelane_b32 v2, s52, 52
	v_writelane_b32 v2, s53, 53
	v_writelane_b32 v2, s54, 54
	v_writelane_b32 v2, s55, 55
	v_writelane_b32 v2, s56, 56
	v_writelane_b32 v2, s57, 57
	v_writelane_b32 v2, s58, 58
	v_writelane_b32 v2, s59, 59
	v_writelane_b32 v2, s60, 60
	v_writelane_b32 v2, s61, 61
	v_writelane_b32 v2, s62, 62
	v_writelane_b32 v2, s63, 63
	v_writelane_b32 v3, s64, 0
	v_writelane_b32 v3, s65, 1
	v_writelane_b32 v3, s66, 2
	v_writelane_b32 v3, s67, 3
	v_writelane_b32 v3, s68, 4
	v_writelane_b32 v3, s69, 5
	v_writelane_b32 v3, s70, 6
	v_writelane_b32 v3, s71, 7
	v_writelane_b32 v3, s72, 8
	v_writelane_b32 v3, s73, 9
	v_writelane_b32 v3, s74, 10
	v_writelane_b32 v3, s75, 11
	v_writelane_b32 v3, s76, 12
	v_writelane_b32 v3, s77, 13
	v_writelane_b32 v3, s78, 14
	v_writelane_b32 v3, s79, 15
	v_writelane_b32 v3, s80, 16
	v_writelane_b32 v3, s81, 17
	v_writelane_b32 v3, s82, 18
	v_writelane_b32 v3, s83, 19
	v_writelane_b32 v3, s84, 20
	v_writelane_b32 v3, s85, 21
	v_writelane_b32 v3, s86, 22
	v_writelane_b32 v3, s87, 23
	v_writelane_b32 v3, s88, 24
	v_writelane_b32 v3, s89, 25
	v_writelane_b32 v3, s90, 26
	v_writelane_b32 v3, s91, 27
	v_writelane_b32 v3, s92, 28
	v_writelane_b32 v3, s93, 29
	v_writelane_b32 v3, s94, 30
	v_writelane_b32 v3, s95, 31
	v_writelane_b32 v3, s96, 32
	v_writelane_b32 v3, s97, 33
	s_lshl_b32 s2, s97, 11
	v_lshl_add_u32 v4, v0, 2, s2
	s_add_u32 s2, s76, 0x30c00000
	s_addc_u32 s3, s77, 0
	global_store_dword v4, v2, s[2:3]
	s_add_u32 s2, s2, 0x80000
	s_addc_u32 s3, s3, 0
	global_store_dword v4, v3, s[2:3]
	s_add_u32 s2, s2, 0x80000
	s_addc_u32 s3, s3, 0
	global_store_dword v4, v0, s[2:3]
	s_add_u32 s2, s2, 0x80000
	s_addc_u32 s3, s3, 0
	global_store_dword v4, v1, s[2:3]
	s_add_u32 s2, s2, 0x80000
	s_addc_u32 s3, s3, 0
	global_store_dword v4, v5, s[2:3]
	s_add_u32 s2, s2, 0x80000
	s_addc_u32 s3, s3, 0
	global_store_dword v4, v6, s[2:3]
	s_add_u32 s2, s2, 0x80000
	s_addc_u32 s3, s3, 0
	global_store_dword v4, v8, s[2:3]
	s_add_u32 s2, s2, 0x80000
	s_addc_u32 s3, s3, 0
	global_store_dword v4, v36, s[2:3]
	s_add_u32 s2, s2, 0x80000
	s_addc_u32 s3, s3, 0
	global_store_dword v4, v37, s[2:3]
	s_add_u32 s2, s2, 0x80000
	s_addc_u32 s3, s3, 0
	global_store_dword v4, v38, s[2:3]
	s_add_u32 s2, s2, 0x80000
	s_addc_u32 s3, s3, 0
	global_store_dword v4, v39, s[2:3]
	s_add_u32 s2, s2, 0x80000
	s_addc_u32 s3, s3, 0
	global_store_dword v4, v40, s[2:3]
	s_add_u32 s2, s2, 0x80000
	s_addc_u32 s3, s3, 0
	global_store_dword v4, v41, s[2:3]
	s_add_u32 s2, s2, 0x80000
	s_addc_u32 s3, s3, 0
	global_store_dword v4, v42, s[2:3]
	s_add_u32 s2, s2, 0x80000
	s_addc_u32 s3, s3, 0
	global_store_dword v4, v43, s[2:3]
	s_add_u32 s2, s2, 0x80000
	s_addc_u32 s3, s3, 0
	global_store_dword v4, v44, s[2:3]
	s_add_u32 s2, s2, 0x80000
	s_addc_u32 s3, s3, 0
	global_store_dword v4, v45, s[2:3]
	s_add_u32 s2, s2, 0x80000
	s_addc_u32 s3, s3, 0
	global_store_dword v4, v50, s[2:3]
	s_add_u32 s2, s2, 0x80000
	s_addc_u32 s3, s3, 0
	global_store_dword v4, v51, s[2:3]
	s_add_u32 s2, s2, 0x80000
	s_addc_u32 s3, s3, 0
	global_store_dword v4, v52, s[2:3]
	s_add_u32 s2, s2, 0x80000
	s_addc_u32 s3, s3, 0
	global_store_dword v4, v53, s[2:3]
	s_add_u32 s2, s2, 0x80000
	s_addc_u32 s3, s3, 0
	global_store_dword v4, v54, s[2:3]
	s_add_u32 s2, s2, 0x80000
	s_addc_u32 s3, s3, 0
	global_store_dword v4, v55, s[2:3]
	s_add_u32 s2, s2, 0x80000
	s_addc_u32 s3, s3, 0
	global_store_dword v4, v56, s[2:3]
	s_add_u32 s2, s2, 0x80000
	s_addc_u32 s3, s3, 0
	global_store_dword v4, v57, s[2:3]
	s_add_u32 s2, s2, 0x80000
	s_addc_u32 s3, s3, 0
	global_store_dword v4, v62, s[2:3]
	s_add_u32 s2, s2, 0x80000
	s_addc_u32 s3, s3, 0
	global_store_dword v4, v63, s[2:3]
	s_add_u32 s2, s2, 0x80000
	s_addc_u32 s3, s3, 0
	global_store_dword v4, v64, s[2:3]
	s_add_u32 s2, s2, 0x80000
	s_addc_u32 s3, s3, 0
	global_store_dword v4, v65, s[2:3]
	s_add_u32 s2, s2, 0x80000
	s_addc_u32 s3, s3, 0
	global_store_dword v4, v70, s[2:3]
	s_add_u32 s2, s2, 0x80000
	s_addc_u32 s3, s3, 0
	global_store_dword v4, v71, s[2:3]
	s_add_u32 s2, s2, 0x80000
	s_addc_u32 s3, s3, 0
	global_store_dword v4, v72, s[2:3]
	s_add_u32 s2, s2, 0x80000
	s_addc_u32 s3, s3, 0
	global_store_dword v4, v73, s[2:3]
	s_add_u32 s2, s2, 0x80000
	s_addc_u32 s3, s3, 0
	global_store_dword v4, v82, s[2:3]
	s_add_u32 s2, s2, 0x80000
	s_addc_u32 s3, s3, 0
	global_store_dword v4, v83, s[2:3]
	s_add_u32 s2, s2, 0x80000
	s_addc_u32 s3, s3, 0
	global_store_dword v4, v84, s[2:3]
	s_add_u32 s2, s2, 0x80000
	s_addc_u32 s3, s3, 0
	global_store_dword v4, v85, s[2:3]
	s_add_u32 s2, s2, 0x80000
	s_addc_u32 s3, s3, 0
	global_store_dword v4, v88, s[2:3]
	s_add_u32 s2, s2, 0x80000
	s_addc_u32 s3, s3, 0
	global_store_dword v4, v89, s[2:3]
	s_add_u32 s2, s2, 0x80000
	s_addc_u32 s3, s3, 0
	global_store_dword v4, v94, s[2:3]
	s_add_u32 s2, s2, 0x80000
	s_addc_u32 s3, s3, 0
	global_store_dword v4, v95, s[2:3]
	s_add_u32 s2, s2, 0x80000
	s_addc_u32 s3, s3, 0
	global_store_dword v4, v96, s[2:3]
	s_add_u32 s2, s2, 0x80000
	s_addc_u32 s3, s3, 0
	global_store_dword v4, v97, s[2:3]
	s_add_u32 s2, s2, 0x80000
	s_addc_u32 s3, s3, 0
	global_store_dword v4, v102, s[2:3]
	s_add_u32 s2, s2, 0x80000
	s_addc_u32 s3, s3, 0
	global_store_dword v4, v103, s[2:3]
	s_add_u32 s2, s2, 0x80000
	s_addc_u32 s3, s3, 0
	global_store_dword v4, v104, s[2:3]
	s_add_u32 s2, s2, 0x80000
	s_addc_u32 s3, s3, 0
	global_store_dword v4, v105, s[2:3]
	s_add_u32 s2, s2, 0x80000
	s_addc_u32 s3, s3, 0
	global_store_dword v4, v122, s[2:3]
	s_add_u32 s2, s2, 0x80000
	s_addc_u32 s3, s3, 0
	global_store_dword v4, v123, s[2:3]
	s_add_u32 s2, s2, 0x80000
	s_addc_u32 s3, s3, 0
	global_store_dword v4, v124, s[2:3]
	s_add_u32 s2, s2, 0x80000
	s_addc_u32 s3, s3, 0
	global_store_dword v4, v125, s[2:3]
	s_add_u32 s2, s2, 0x80000
	s_addc_u32 s3, s3, 0
	global_store_dword v4, v170, s[2:3]
	s_add_u32 s2, s2, 0x80000
	s_addc_u32 s3, s3, 0
	global_store_dword v4, v171, s[2:3]
	s_add_u32 s2, s2, 0x80000
	s_addc_u32 s3, s3, 0
	global_store_dword v4, v172, s[2:3]
	s_add_u32 s2, s2, 0x80000
	s_addc_u32 s3, s3, 0
	global_store_dword v4, v173, s[2:3]
	s_add_u32 s2, s2, 0x80000
	s_addc_u32 s3, s3, 0
	global_store_dword v4, v174, s[2:3]
	s_add_u32 s2, s2, 0x80000
	s_addc_u32 s3, s3, 0
	global_store_dword v4, v175, s[2:3]
	s_add_u32 s2, s2, 0x80000
	s_addc_u32 s3, s3, 0
	global_store_dword v4, v195, s[2:3]
	s_add_u32 s2, s2, 0x80000
	s_addc_u32 s3, s3, 0
	global_store_dword v4, v197, s[2:3]
	s_add_u32 s2, s2, 0x80000
	s_addc_u32 s3, s3, 0
	global_store_dword v4, v254, s[2:3]
	s_add_u32 s2, s2, 0x80000
	s_addc_u32 s3, s3, 0
	global_store_dword v4, v255, s[2:3]
	s_waitcnt vmcnt(0)
	v_lshlrev_b32_e32 v4, 2, v0
	v_add_u32_e32 v4, 0x22080, v4
	ds_read_b32 v7, v4 offset:4096
	ds_read_b32 v254, v4 offset:2048
	s_waitcnt lgkmcnt(0)
	s_sub_i32 s2, s97, 0x70
	v_readlane_b32 s0, v7, 0
	v_readlane_b32 s1, v7, 1
	v_readlane_b32 s20, v7, 2
	v_readlane_b32 s76, v7, 3
	v_readlane_b32 s77, v7, 4
	s_movk_i32 s96, 0x90
	s_mov_b32 s97, s2
	s_mov_b32 s32, 1
	s_nop 4
	s_branch .Lmode_reentry

.LBB0_649:
	s_or_b64 exec, exec, s[0:1]
	v_readlane_b32 s0, v254, 10
	v_readlane_b32 s2, v254, 12
	s_cmpk_lt_i32 s97, 0x70
	s_cbranch_scc1 .Lp5_skip
	s_bitcmp0_b32 s2, 0
.Lp5_skip:
	s_waitcnt vmcnt(0)
	s_barrier
	v_readlane_b32 s1, v254, 11
	v_readlane_b32 s3, v254, 13
	s_cbranch_scc1 .LBB0_738
	v_mov_b32_e32 v161, 0
	s_mov_b64 s[0:1], exec
	v_readlane_b32 s2, v254, 17
	v_readlane_b32 s3, v254, 18
	s_and_b64 s[2:3], s[0:1], s[2:3]
	s_mov_b64 exec, s[2:3]
	s_cbranch_execz .LBB0_654
	s_mov_b64 s[4:5], exec
	v_mbcnt_lo_u32_b32 v2, s4, 0
	v_mbcnt_hi_u32_b32 v2, s5, v2
	v_cmp_eq_u32_e32 vcc, 0, v2
	s_and_saveexec_b64 s[2:3], vcc
	s_cbranch_execz .LBB0_653
	s_bcnt1_i32_b64 s4, s[4:5]
	v_mov_b32_e32 v3, 0
	v_mov_b32_e32 v4, s4
	global_atomic_add v3, v3, v4, s[76:77] offset:512 sc0

.LBB0_738:
	s_cmpk_lt_i32 s97, 0x70
	s_cselect_b32 s3, 0, 0x2a0
	s_add_i32 s3, s3, s97
	s_cmpk_lt_i32 s3, 0x3e0
	s_cselect_b64 s[0:1], -1, 0
	s_cmpk_gt_i32 s3, 0x3df
	v_readfirstlane_b32 s6, v0
	s_cbranch_scc1 .LBB0_743
	s_and_b32 s2, s3, 7
	s_mul_i32 s5, s2, 0x7c
	s_lshr_b32 s2, s3, 3
	s_add_i32 s5, s5, s2
	s_cmpk_gt_i32 s5, 0x37f
	s_cbranch_scc0 .LBB0_741
	s_add_i32 s2, s5, 0xfffffc80
	s_lshr_b32 s3, s2, 4
	s_and_b32 s4, s5, 15
	s_cmp_lt_u32 s2, 32
	s_cselect_b32 s2, 14, 28
	s_add_i32 s14, s2, s3
	s_add_i32 s2, s4, 24
	s_cmp_lt_u32 s4, 8
	s_cselect_b32 s4, s4, s2
	s_cbranch_execz .LBB0_742
	s_branch .LBB0_743

.LBB0_749:
	s_add_i32 s53, s53, 1
	v_readlane_b32 s16, v254, 56
	v_readlane_b32 s6, v254, 60
	s_nop 0
	s_cmpk_lt_i32 s6, 0x70
	s_cbranch_scc0 .Li8_clsB
	s_mul_i32 s5, s53, 0x70
	s_add_i32 s5, s5, s6
	s_cmpk_lt_i32 s53, 7
	s_cselect_b32 s5, s5, 0x3e0
	s_branch .Li8_join
.Li8_clsB:
	s_mul_i32 s5, s53, 0x90
	s_add_i32 s5, s5, s6
	s_add_i32 s5, s5, 0x2a0
.Li8_join:
	s_cmpk_lt_i32 s5, 0x3e0
	s_cselect_b64 s[28:29], -1, 0
	s_cmpk_gt_i32 s5, 0x3df
	v_readlane_b32 s17, v254, 57
	s_cbranch_scc1 .LBB0_754
	s_and_b32 s6, s5, 7
	s_mulk_i32 s6, 0x7c
	s_ashr_i32 s5, s5, 3
	s_add_i32 s5, s6, s5
	s_cmpk_gt_i32 s5, 0x37f
	s_mov_b64 s[38:39], -1
	s_cbranch_scc0 .LBB0_752
	s_add_i32 s6, s5, 0xfffffc80
	s_lshr_b32 s16, s6, 4
	s_and_b32 s17, s5, 15
	s_cmp_lt_u32 s6, 32
	s_cselect_b32 s6, 14, 28
	s_add_i32 s20, s6, s16
	s_add_i32 s6, s17, 24
	s_cmp_lt_u32 s17, 8
	s_cselect_b32 s34, s17, s6
	s_mov_b64 s[38:39], 0
